# diff-attention row-sum MFMAs use a ones operand that is non-zero only in column 0 (row sums broadcast once per unit by DPP before 1/l): same sums, less switching in the power-limited loop
# baseline (speedup 1.0000x reference)
; __device__ __forceinline__ void attn_unit_d16(const UnitDesc& U, char* shm, float lam, const float* subw) {
;     ...
;     const int tid = threadIdx.x, lane = tid & 63, c16 = lane & 15, g = lane >> 4; const int wid = __builtin_amdgcn_readfirstlane(tid >> 6);
;     const unsigned lds0 = (unsigned)(uintptr_t)shm;
;     const int map = wid >> 2;
;     unsigned koff, voff; unsigned kdst[NPK], vdst[NPV];
;     { const int key = 8 * wid + (lane >> 3), pp = lane & 7;
;       koff = (unsigned)(key * U.KP + (pp ^ ((key >> 1) & 7)) * 8) * 2u; voff = (unsigned)(key * U.VP + ((((pp >> 1) ^ ((key >> 1) & 3)) << 1) + (pp & 1)) * 8) * 2u;
; #pragma unroll
;       for (int pc = 0; pc < NPK; ++pc) kdst[pc] = lds0 + LDS_K + pc * 8192 + wid * 1024;
; #pragma unroll
;       for (int pc = 0; pc < NPV; ++pc) vdst[pc] = lds0 + LDS_V + pc * 8192 + wid * 1024; }
;     ...
;     const lds_cptr shm3 = (lds_cptr)shm;
;     lds_cptr kpb[2];
; #pragma unroll
;     for (int ds = 0; ds < 2; ++ds) kpb[ds] = shm3 + LDS_K + map * 8192 + c16 * 128 + (((4 * ds + g) ^ (c16 >> 1)) << 4);
;     lds_cptr vpb[4];
;     { const int q4 = c16 >> 2, p = c16 & 3, ko = 4 * g + q4, swz = (ko >> 1) & 3;
; #pragma unroll
;       for (int b = 0; b < 4; ++b) vpb[b] = shm3 + LDS_V + ko * 128 + ((b ^ swz) << 5) + p * 8; }
;     bf16x8 qr[2][2];
; #pragma unroll
;     for (int qt = 0; qt < 2; ++qt)
; #pragma unroll
;         for (int ds = 0; ds < 2; ++ds) qr[qt][ds] = *reinterpret_cast<const bf16x8*>(U.Qw + (size_t)(16 * qt + c16) * 512 + 32 * ds + 8 * g);
;     const f32x4v zero4 = {0.f, 0.f, 0.f, 0.f};
;     f32x4v o[2][8], S[4][2], ls[2];
; #pragma unroll
;     for (int qt = 0; qt < 2; ++qt) { ls[qt] = zero4;
; #pragma unroll
;         for (int dt = 0; dt < 8; ++dt) o[qt][dt] = zero4; }
;     const bf16x8 onesb = {(short)0x3F80, (short)0x3F80, (short)0x3F80, (short)0x3F80, (short)0x3F80, (short)0x3F80, (short)0x3F80, (short)0x3F80};
.LBB0_423:
	v_readlane_b32 s0, v252, 0
	s_cmpk_gt_i32 s0, 0xbff
	s_cbranch_scc1 .LBB0_449
	v_lshlrev_b32_e32 v0, 4, v180
	v_and_b32_e32 v1, 0x3c0, v0
	v_xor_b32_e32 v0, v0, v180
	v_and_or_b32 v190, v0, 48, v1
	v_lshlrev_b32_e32 v0, 6, v180
	v_bfe_u32 v2, v180, 2, 2
	v_and_b32_e32 v182, 0x7c0, v0
	v_lshrrev_b32_e32 v0, 4, v180
	v_and_b32_e32 v1, 2, v0
	v_bitop3_b32 v0, v0, v2, 2 bitop3:0x6c
	v_lshlrev_b32_e32 v4, 4, v0
	v_bitop3_b32 v0, v1, v2, 1 bitop3:0x36
	v_mov_b32_e32 v183, 0
	v_add_u32_e32 v3, 0, v182
	v_lshlrev_b32_e32 v5, 4, v0
	v_lshl_add_u64 v[0:1], s[28:29], 0, v[182:183]
	v_and_b32_e32 v182, 32, v180
	v_lshrrev_b32_e32 v191, 3, v193
	v_lshl_add_u64 v[184:185], v[0:1], 0, v[182:183]
	v_xor_b32_e32 v1, v191, v180
	v_and_b32_e32 v6, 1, v180
	v_and_or_b32 v1, v1, 6, v6
	v_lshrrev_b32_e32 v6, 4, v193
	v_lshlrev_b32_e32 v192, 4, v1
	v_bfe_u32 v1, v180, 1, 3
	v_xor_b32_e32 v7, v6, v1
	v_bitop3_b32 v1, v6, v1, 4 bitop3:0x36
	v_lshlrev_b32_e32 v195, 4, v7
	v_lshlrev_b32_e32 v196, 4, v1
	v_lshl_or_b32 v1, v6, 2, v2
	v_lshlrev_b32_e32 v7, 3, v180
	v_readlane_b32 s0, v252, 9
	v_lshlrev_b32_e32 v2, 7, v1
	s_add_i32 s3, 0, 0x10000
	v_and_b32_e32 v7, 24, v7
	s_waitcnt lgkmcnt(0)
	s_lshl_b32 s42, s0, 5
	s_movk_i32 s0, 0x60
	s_lshr_b32 s1, s33, 2
	v_add3_u32 v7, s3, v2, v7
	v_lshlrev_b32_e32 v1, 4, v1
	v_mov_b32_e32 v2, 0x60
	s_and_b32 s43, s42, 0x60
	s_and_b32 s1, s1, 0x3fffffc0
	v_and_b32_e32 v0, 15, v180
	v_and_b32_e32 v8, 0x60, v1
	v_bitop3_b32 v9, v1, 32, v2 bitop3:0x6c
	v_bitop3_b32 v10, v1, 64, v2 bitop3:0x6c
	v_bitop3_b32 v1, v1, s0, v1 bitop3:0xc
	v_lshl_add_u32 v194, v0, 7, 0
	v_lshlrev_b32_e32 v0, 9, v0
	v_lshlrev_b32_e32 v2, 3, v6
	s_add_u32 s3, s58, 0x11060000
	s_mov_b32 s4, 0x3f803f80
	v_and_b32_e32 v248, 15, v193
	v_sub_u32_e32 v248, 0, v248
	v_ashrrev_i32_e32 v248, 31, v248
	v_not_b32_e32 v248, v248
	v_and_b32_e32 v248, 0x3f803f80, v248
	v_mov_b32_e32 v249, v248
	v_mov_b32_e32 v250, v248
	v_mov_b32_e32 v251, v248
	v_add_u32_e32 v206, v7, v1
	v_mbcnt_lo_u32_b32 v1, -1, 0
	s_mov_b32 s9, 0
	s_addc_u32 s44, s59, 0
	s_movk_i32 s45, 0x4000
	s_movk_i32 s46, 0x3000
	v_mov_b32_e32 v197, 0x7c7c7c7c
	v_mov_b32_e32 v198, 0x7f7f7f7f
	s_movk_i32 s47, 0x70
	s_lshl_b32 s48, s1, 1
	v_lshlrev_b32_e32 v186, 1, v2
	v_lshlrev_b32_e32 v188, 1, v0
	v_mov_b32_e32 v199, 0x358637bd
	s_mov_b32 s49, 0xf800000
	v_mov_b32_e32 v200, 0x260
	s_mov_b32 s50, 0x3f24fd5c
	v_mov_b32_e32 v0, -4.0
	v_mov_b32_e32 v114, 0x38383838
	v_add_u32_e32 v201, v3, v4
	v_add_u32_e32 v202, v3, v5
	v_add_u32_e32 v203, v7, v8
	v_add_u32_e32 v204, v7, v9
	v_add_u32_e32 v205, v7, v10
	s_mov_b32 s5, s4
	s_mov_b32 s6, s4
	s_mov_b32 s7, s4
	v_mbcnt_hi_u32_b32 v207, -1, v1
	v_readlane_b32 s51, v252, 0
	s_branch .LBB0_427

.LBB0_444:
	ds_read_b64_tr_b16 v[158:159], v203
	ds_read_b64_tr_b16 v[160:161], v203 offset:2048
	s_waitcnt lgkmcnt(9)
	v_mfma_f32_16x16x32_bf16 v[140:143], v[110:113], v[10:13], 0
	s_waitcnt lgkmcnt(7)
	v_mfma_f32_16x16x32_bf16 v[152:155], v[26:29], v[14:17], v[140:143]
	ds_read_b64_tr_b16 v[162:163], v204
	ds_read_b64_tr_b16 v[164:165], v204 offset:2048
	v_mfma_f32_16x16x32_bf16 v[110:113], v[110:113], v[18:21], 0
	v_mfma_f32_16x16x32_bf16 v[144:147], v[26:29], v[22:25], v[110:113]
	ds_read_b64_tr_b16 v[166:167], v205
	ds_read_b64_tr_b16 v[168:169], v205 offset:2048
	v_mfma_f32_16x16x32_bf16 v[26:29], v[116:119], v[10:13], 0
	s_waitcnt lgkmcnt(10)
	v_mfma_f32_16x16x32_bf16 v[148:151], v[120:123], v[14:17], v[26:29]
	ds_read_b64_tr_b16 v[170:171], v206
	ds_read_b64_tr_b16 v[172:173], v206 offset:2048
	v_mfma_f32_16x16x32_bf16 v[26:29], v[116:119], v[18:21], 0
	v_mfma_f32_16x16x32_bf16 v[140:143], v[120:123], v[22:25], v[26:29]
	ds_read_b64_tr_b16 v[174:175], v203 offset:8192
	ds_read_b64_tr_b16 v[176:177], v203 offset:10240
	s_waitcnt lgkmcnt(13)
	v_mfma_f32_16x16x32_bf16 v[26:29], v[124:127], v[10:13], 0
	s_waitcnt lgkmcnt(11)
	v_mfma_f32_16x16x32_bf16 v[110:113], v[132:135], v[14:17], v[26:29]
	ds_read_b64_tr_b16 v[208:209], v204 offset:8192
	ds_read_b64_tr_b16 v[210:211], v204 offset:10240
	v_mfma_f32_16x16x32_bf16 v[26:29], v[124:127], v[18:21], 0
	v_mfma_f32_16x16x32_bf16 v[116:119], v[132:135], v[22:25], v[26:29]
	ds_read_b64_tr_b16 v[132:133], v205 offset:8192
	ds_read_b64_tr_b16 v[134:135], v205 offset:10240
	v_mfma_f32_16x16x32_bf16 v[26:29], v[128:131], v[10:13], 0
	s_waitcnt lgkmcnt(14)
	v_mfma_f32_16x16x32_bf16 v[120:123], v[136:139], v[14:17], v[26:29]
	ds_read_b64_tr_b16 v[212:213], v206 offset:8192
	ds_read_b64_tr_b16 v[214:215], v206 offset:10240
	v_mfma_f32_16x16x32_bf16 v[26:29], v[128:131], v[18:21], 0
	v_mfma_f32_16x16x32_bf16 v[124:127], v[136:139], v[22:25], v[26:29]
	s_add_u32 s68, s14, 0xfcfe0000
	s_addc_u32 s69, s15, -1
	s_mov_b32 s74, m0
	s_mov_b32 m0, s30
	s_nop 0
	global_load_lds_dwordx4 v157, s[68:69]
	s_mov_b32 m0, s74
	s_add_u32 s68, s14, 0xfcfe0080
	s_addc_u32 s69, s15, -1
	s_mov_b32 s74, m0
	s_mov_b32 m0, s31
	s_nop 0
	global_load_lds_dwordx4 v157, s[68:69]
	s_mov_b32 m0, s74
	s_add_u32 s74, s14, 0xfffd0000
	s_addc_u32 s75, s15, -1
	s_add_i32 s68, s38, 0xc000
	s_mov_b32 s69, m0
	s_mov_b32 m0, s68
	s_nop 0
	global_load_lds_dwordx4 v156, s[74:75]
	s_mov_b32 m0, s69
	s_add_u32 s74, s14, 0xfffd0080
	s_addc_u32 s75, s15, -1
	s_add_i32 s69, s39, 0xc000
	s_mov_b32 s76, m0
	s_mov_b32 m0, s69
	s_nop 0
	global_load_lds_dwordx4 v156, s[74:75]
	s_mov_b32 m0, s76
	ds_read_b64_tr_b16 v[128:129], v203 offset:4096
	ds_read_b64_tr_b16 v[130:131], v203 offset:6144
	v_mov_b64_e32 v[28:29], v[250:251]
	v_mov_b64_e32 v[26:27], v[248:249]
	s_waitcnt lgkmcnt(14)
	v_mfma_f32_16x16x32_bf16 v[98:101], v[6:9], v[158:161], v[98:101]
	v_exp_f32_e32 v152, v152
	v_mfma_f32_16x16x32_bf16 v[106:109], v[6:9], v[26:29], v[106:109]
	v_mfma_f32_16x16x32_bf16 v[102:105], v[2:5], v[26:29], v[102:105]
	v_exp_f32_e32 v153, v153
	v_mfma_f32_16x16x32_bf16 v[90:93], v[2:5], v[158:161], v[90:93]
	ds_read_b64_tr_b16 v[136:137], v204 offset:4096
	ds_read_b64_tr_b16 v[138:139], v204 offset:6144
	v_mfma_f32_16x16x32_bf16 v[94:97], v[6:9], v[162:165], v[94:97]
	v_exp_f32_e32 v154, v154
	v_mfma_f32_16x16x32_bf16 v[82:85], v[2:5], v[162:165], v[82:85]
	v_exp_f32_e32 v155, v155
	ds_read_b64_tr_b16 v[158:159], v205 offset:4096
	ds_read_b64_tr_b16 v[160:161], v205 offset:6144
	s_waitcnt lgkmcnt(14)
	v_mfma_f32_16x16x32_bf16 v[86:89], v[6:9], v[166:169], v[86:89]
	v_exp_f32_e32 v144, v144
	s_nop 0
	v_exp_f32_e32 v145, v145
	v_mfma_f32_16x16x32_bf16 v[162:165], v[2:5], v[166:169], v[74:77]
	ds_read_b64_tr_b16 v[166:167], v206 offset:4096
	ds_read_b64_tr_b16 v[168:169], v206 offset:6144
	v_exp_f32_e32 v146, v146
	v_mfma_f32_16x16x32_bf16 v[216:219], v[6:9], v[170:173], v[78:81]
	s_nop 0
	v_exp_f32_e32 v147, v147
	v_mfma_f32_16x16x32_bf16 v[170:173], v[2:5], v[170:173], v[66:69]
	ds_read_b64_tr_b16 v[220:221], v203 offset:12288
	ds_read_b64_tr_b16 v[222:223], v203 offset:14336
	v_exp_f32_e32 v148, v148
	s_waitcnt lgkmcnt(14)
	v_mfma_f32_16x16x32_bf16 v[224:227], v[6:9], v[174:177], v[70:73]
	v_mfma_f32_16x16x32_bf16 v[58:61], v[2:5], v[174:177], v[58:61]
	v_exp_f32_e32 v149, v149
	ds_read_b64_tr_b16 v[174:175], v204 offset:12288
	ds_read_b64_tr_b16 v[176:177], v204 offset:14336
	v_exp_f32_e32 v150, v150
	v_mfma_f32_16x16x32_bf16 v[228:231], v[6:9], v[208:211], v[62:65]
	v_mfma_f32_16x16x32_bf16 v[50:53], v[2:5], v[208:211], v[50:53]
	v_exp_f32_e32 v151, v151
	ds_read_b64_tr_b16 v[208:209], v205 offset:12288
	ds_read_b64_tr_b16 v[210:211], v205 offset:14336
	s_waitcnt lgkmcnt(14)
	v_mfma_f32_16x16x32_bf16 v[54:57], v[6:9], v[132:135], v[54:57]
	v_exp_f32_e32 v140, v140
	v_mfma_f32_16x16x32_bf16 v[42:45], v[2:5], v[132:135], v[42:45]
	v_exp_f32_e32 v141, v141
	ds_read_b64_tr_b16 v[232:233], v206 offset:12288
	ds_read_b64_tr_b16 v[234:235], v206 offset:14336
	v_mfma_f32_16x16x32_bf16 v[46:49], v[6:9], v[212:215], v[46:49]
	v_exp_f32_e32 v142, v142
	s_nop 0
	v_exp_f32_e32 v143, v143
	v_mfma_f32_16x16x32_bf16 v[212:215], v[2:5], v[212:215], v[38:41]
	s_nop 2
	ds_read_b128 v[38:41], v1 offset:32768
	v_mfma_f32_16x16x32_bf16 v[66:69], v[34:37], v[26:29], v[106:109]
	v_exp_f32_e32 v110, v110
	v_cvt_pk_bf16_f32 v6, v152, v153
	s_waitcnt lgkmcnt(14)
	v_mfma_f32_16x16x32_bf16 v[62:65], v[34:37], v[128:131], v[98:101]
	v_mfma_f32_16x16x32_bf16 v[70:73], v[30:33], v[26:29], v[102:105]
	v_exp_f32_e32 v111, v111
	v_cvt_pk_bf16_f32 v7, v154, v155
	v_mfma_f32_16x16x32_bf16 v[78:81], v[30:33], v[128:131], v[90:93]
	ds_read_b128 v[236:239], v115 offset:32768
	s_waitcnt lgkmcnt(14)
	v_mfma_f32_16x16x32_bf16 v[74:77], v[34:37], v[136:139], v[94:97]
	v_exp_f32_e32 v112, v112
	v_cvt_pk_bf16_f32 v8, v148, v149
	v_mfma_f32_16x16x32_bf16 v[82:85], v[30:33], v[136:139], v[82:85]
	v_exp_f32_e32 v113, v113
	v_cvt_pk_bf16_f32 v9, v150, v151
	ds_read_b128 v[240:243], v1 offset:34816
	s_waitcnt lgkmcnt(13)
	v_mfma_f32_16x16x32_bf16 v[90:93], v[34:37], v[158:161], v[86:89]
	v_exp_f32_e32 v116, v116
	v_cvt_pk_bf16_f32 v2, v144, v145
	v_mfma_f32_16x16x32_bf16 v[94:97], v[30:33], v[158:161], v[162:165]
	v_exp_f32_e32 v117, v117
	v_cvt_pk_bf16_f32 v3, v146, v147
	ds_read_b128 v[158:161], v115 offset:34816
	s_waitcnt lgkmcnt(12)
	v_mfma_f32_16x16x32_bf16 v[98:101], v[34:37], v[166:169], v[216:219]
	v_exp_f32_e32 v118, v118
	v_cvt_pk_bf16_f32 v4, v140, v141
	v_mfma_f32_16x16x32_bf16 v[102:105], v[30:33], v[166:169], v[170:173]
	v_exp_f32_e32 v119, v119
	v_cvt_pk_bf16_f32 v5, v142, v143
	ds_read_b128 v[162:165], v1 offset:36864
	v_exp_f32_e32 v120, v120
	s_waitcnt lgkmcnt(11)
	v_mfma_f32_16x16x32_bf16 v[148:151], v[34:37], v[220:223], v[224:227]
	s_nop 0
	v_exp_f32_e32 v121, v121
	v_mfma_f32_16x16x32_bf16 v[152:155], v[30:33], v[220:223], v[58:61]
	ds_read_b128 v[166:169], v115 offset:36864
	v_exp_f32_e32 v122, v122
	s_waitcnt lgkmcnt(10)
	v_mfma_f32_16x16x32_bf16 v[140:143], v[34:37], v[174:177], v[228:231]
	s_nop 0
	v_exp_f32_e32 v123, v123
	v_mfma_f32_16x16x32_bf16 v[144:147], v[30:33], v[174:177], v[50:53]
	s_nop 2
	ds_read_b128 v[50:53], v1 offset:38912
	s_waitcnt lgkmcnt(9)
	v_mfma_f32_16x16x32_bf16 v[132:135], v[34:37], v[208:211], v[54:57]
	v_exp_f32_e32 v124, v124
	v_mfma_f32_16x16x32_bf16 v[136:139], v[30:33], v[208:211], v[42:45]
	v_exp_f32_e32 v125, v125
	ds_read_b128 v[170:173], v115 offset:38912
	s_waitcnt lgkmcnt(8)
	v_mfma_f32_16x16x32_bf16 v[106:109], v[34:37], v[232:235], v[46:49]
	v_exp_f32_e32 v126, v126
	v_mfma_f32_16x16x32_bf16 v[128:131], v[30:33], v[232:235], v[212:215]
	v_exp_f32_e32 v127, v127
	v_cvt_pk_bf16_f32 v34, v110, v111
	v_cvt_pk_bf16_f32 v35, v112, v113
	v_cvt_pk_bf16_f32 v36, v120, v121
	v_cvt_pk_bf16_f32 v37, v122, v123
	v_cvt_pk_bf16_f32 v30, v116, v117
	v_cvt_pk_bf16_f32 v31, v118, v119
	v_cvt_pk_bf16_f32 v32, v124, v125
	v_cvt_pk_bf16_f32 v33, v126, v127
	s_waitcnt vmcnt(4)
	s_barrier
	ds_read_b64_tr_b16 v[116:117], v203 offset:16384
	ds_read_b64_tr_b16 v[118:119], v203 offset:18432
	s_waitcnt lgkmcnt(9)
	v_mfma_f32_16x16x32_bf16 v[42:45], v[38:41], v[10:13], 0
	s_waitcnt lgkmcnt(8)
	v_mfma_f32_16x16x32_bf16 v[110:113], v[236:239], v[14:17], v[42:45]
	ds_read_b64_tr_b16 v[120:121], v204 offset:16384
	ds_read_b64_tr_b16 v[122:123], v204 offset:18432
	v_mfma_f32_16x16x32_bf16 v[38:41], v[38:41], v[18:21], 0
	v_mfma_f32_16x16x32_bf16 v[58:61], v[236:239], v[22:25], v[38:41]
	ds_read_b64_tr_b16 v[124:125], v205 offset:16384
	ds_read_b64_tr_b16 v[126:127], v205 offset:18432
	s_waitcnt lgkmcnt(11)
	v_mfma_f32_16x16x32_bf16 v[38:41], v[240:243], v[10:13], 0
	s_waitcnt lgkmcnt(10)
	v_mfma_f32_16x16x32_bf16 v[86:89], v[158:161], v[14:17], v[38:41]
	ds_read_b64_tr_b16 v[174:175], v206 offset:16384
	ds_read_b64_tr_b16 v[176:177], v206 offset:18432
	v_mfma_f32_16x16x32_bf16 v[38:41], v[240:243], v[18:21], 0
	v_mfma_f32_16x16x32_bf16 v[54:57], v[158:161], v[22:25], v[38:41]
	ds_read_b64_tr_b16 v[158:159], v203 offset:24576
	ds_read_b64_tr_b16 v[160:161], v203 offset:26624
	s_waitcnt lgkmcnt(13)
	v_mfma_f32_16x16x32_bf16 v[38:41], v[162:165], v[10:13], 0
	s_waitcnt lgkmcnt(12)
	v_mfma_f32_16x16x32_bf16 v[38:41], v[166:169], v[14:17], v[38:41]
	ds_read_b64_tr_b16 v[208:209], v204 offset:24576
	ds_read_b64_tr_b16 v[210:211], v204 offset:26624
	v_mfma_f32_16x16x32_bf16 v[42:45], v[162:165], v[18:21], 0
	v_mfma_f32_16x16x32_bf16 v[42:45], v[166:169], v[22:25], v[42:45]
	ds_read_b64_tr_b16 v[162:163], v205 offset:24576
	ds_read_b64_tr_b16 v[164:165], v205 offset:26624
	s_waitcnt lgkmcnt(14)
	v_mfma_f32_16x16x32_bf16 v[46:49], v[50:53], v[10:13], 0
	v_mfma_f32_16x16x32_bf16 v[46:49], v[170:173], v[14:17], v[46:49]
	ds_read_b64_tr_b16 v[166:167], v206 offset:24576
	ds_read_b64_tr_b16 v[168:169], v206 offset:26624
	v_mfma_f32_16x16x32_bf16 v[50:53], v[50:53], v[18:21], 0
	v_mfma_f32_16x16x32_bf16 v[50:53], v[170:173], v[22:25], v[50:53]
	s_add_u32 s74, s14, 0xfcff0000
	s_addc_u32 s75, s15, -1
	s_mov_b32 s76, m0
	s_mov_b32 m0, s40
	s_nop 0
	global_load_lds_dwordx4 v157, s[74:75]
	s_mov_b32 m0, s76
	s_add_u32 s74, s14, 0xfcff0080
	s_addc_u32 s75, s15, -1
	s_mov_b32 s76, m0
	s_mov_b32 m0, s41
	s_nop 0
	global_load_lds_dwordx4 v157, s[74:75]
	s_mov_b32 m0, s76
	s_add_u32 s74, s14, 0xfffe0000
	s_addc_u32 s75, s15, -1
	s_mov_b32 s76, m0
	s_mov_b32 m0, s38
	s_nop 0
	global_load_lds_dwordx4 v156, s[74:75]
	s_mov_b32 m0, s76
	s_add_u32 s74, s14, 0xfffe0080
	s_addc_u32 s75, s15, -1
	s_mov_b32 s76, m0
	s_mov_b32 m0, s39
	s_nop 0
	global_load_lds_dwordx4 v156, s[74:75]
	s_mov_b32 m0, s76
	ds_read_b64_tr_b16 v[170:171], v203 offset:20480
	ds_read_b64_tr_b16 v[172:173], v203 offset:22528
	v_mfma_f32_16x16x32_bf16 v[66:69], v[6:9], v[26:29], v[66:69]
	v_exp_f32_e32 v110, v110
	s_waitcnt lgkmcnt(14)
	v_mfma_f32_16x16x32_bf16 v[62:65], v[6:9], v[116:119], v[62:65]
	v_mfma_f32_16x16x32_bf16 v[70:73], v[2:5], v[26:29], v[70:73]
	v_exp_f32_e32 v111, v111
	v_mfma_f32_16x16x32_bf16 v[78:81], v[2:5], v[116:119], v[78:81]
	ds_read_b64_tr_b16 v[116:117], v204 offset:20480
	ds_read_b64_tr_b16 v[118:119], v204 offset:22528
	v_mfma_f32_16x16x32_bf16 v[74:77], v[6:9], v[120:123], v[74:77]
	v_exp_f32_e32 v112, v112
	v_mfma_f32_16x16x32_bf16 v[82:85], v[2:5], v[120:123], v[82:85]
	v_exp_f32_e32 v113, v113
	ds_read_b64_tr_b16 v[120:121], v205 offset:20480
	ds_read_b64_tr_b16 v[122:123], v205 offset:22528
	s_waitcnt lgkmcnt(14)
	v_mfma_f32_16x16x32_bf16 v[90:93], v[6:9], v[124:127], v[90:93]
	v_exp_f32_e32 v58, v58
	v_mfma_f32_16x16x32_bf16 v[94:97], v[2:5], v[124:127], v[94:97]
	v_exp_f32_e32 v59, v59
	ds_read_b64_tr_b16 v[124:125], v206 offset:20480
	ds_read_b64_tr_b16 v[126:127], v206 offset:22528
	v_mfma_f32_16x16x32_bf16 v[98:101], v[6:9], v[174:177], v[98:101]
	v_exp_f32_e32 v60, v60
	v_mfma_f32_16x16x32_bf16 v[102:105], v[2:5], v[174:177], v[102:105]
	v_exp_f32_e32 v61, v61
	ds_read_b64_tr_b16 v[174:175], v203 offset:28672
	ds_read_b64_tr_b16 v[176:177], v203 offset:30720
	v_exp_f32_e32 v86, v86
	s_waitcnt lgkmcnt(14)
	v_mfma_f32_16x16x32_bf16 v[148:151], v[6:9], v[158:161], v[148:151]
	s_nop 0
	v_exp_f32_e32 v87, v87
	v_mfma_f32_16x16x32_bf16 v[152:155], v[2:5], v[158:161], v[152:155]
	ds_read_b64_tr_b16 v[158:159], v204 offset:28672
	ds_read_b64_tr_b16 v[160:161], v204 offset:30720
	v_exp_f32_e32 v88, v88
	v_mfma_f32_16x16x32_bf16 v[212:215], v[6:9], v[208:211], v[140:143]
	s_nop 0
	v_exp_f32_e32 v89, v89
	v_mfma_f32_16x16x32_bf16 v[208:211], v[2:5], v[208:211], v[144:147]
	ds_read_b64_tr_b16 v[216:217], v205 offset:28672
	ds_read_b64_tr_b16 v[218:219], v205 offset:30720
	v_exp_f32_e32 v54, v54
	s_waitcnt lgkmcnt(14)
	v_mfma_f32_16x16x32_bf16 v[220:223], v[6:9], v[162:165], v[132:135]
	s_nop 0
	v_exp_f32_e32 v55, v55
	v_mfma_f32_16x16x32_bf16 v[162:165], v[2:5], v[162:165], v[136:139]
	ds_read_b64_tr_b16 v[224:225], v206 offset:28672
	ds_read_b64_tr_b16 v[226:227], v206 offset:30720
	v_mfma_f32_16x16x32_bf16 v[106:109], v[6:9], v[166:169], v[106:109]
	v_exp_f32_e32 v56, v56
	s_nop 0
	v_exp_f32_e32 v57, v57
	v_mfma_f32_16x16x32_bf16 v[166:169], v[2:5], v[166:169], v[128:131]
	ds_read_b128 v[144:147], v1 offset:49152
	v_mfma_f32_16x16x32_bf16 v[66:69], v[34:37], v[26:29], v[66:69]
	v_exp_f32_e32 v38, v38
	v_cvt_pk_bf16_f32 v6, v110, v111
	s_waitcnt lgkmcnt(14)
	v_mfma_f32_16x16x32_bf16 v[62:65], v[34:37], v[170:173], v[62:65]
	v_mfma_f32_16x16x32_bf16 v[70:73], v[30:33], v[26:29], v[70:73]
	v_exp_f32_e32 v39, v39
	v_cvt_pk_bf16_f32 v7, v112, v113
	v_mfma_f32_16x16x32_bf16 v[78:81], v[30:33], v[170:173], v[78:81]
	ds_read_b128 v[170:173], v115 offset:49152
	s_waitcnt lgkmcnt(14)
	v_mfma_f32_16x16x32_bf16 v[74:77], v[34:37], v[116:119], v[74:77]
	v_exp_f32_e32 v40, v40
	v_cvt_pk_bf16_f32 v8, v86, v87
	v_mfma_f32_16x16x32_bf16 v[82:85], v[30:33], v[116:119], v[82:85]
	v_exp_f32_e32 v41, v41
	v_cvt_pk_bf16_f32 v9, v88, v89
	ds_read_b128 v[228:231], v1 offset:51200
	s_waitcnt lgkmcnt(13)
	v_mfma_f32_16x16x32_bf16 v[90:93], v[34:37], v[120:123], v[90:93]
	v_exp_f32_e32 v42, v42
	v_cvt_pk_bf16_f32 v2, v58, v59
	v_mfma_f32_16x16x32_bf16 v[94:97], v[30:33], v[120:123], v[94:97]
	v_exp_f32_e32 v43, v43
	v_cvt_pk_bf16_f32 v3, v60, v61
	ds_read_b128 v[232:235], v115 offset:51200
	s_waitcnt lgkmcnt(12)
	v_mfma_f32_16x16x32_bf16 v[98:101], v[34:37], v[124:127], v[98:101]
	v_exp_f32_e32 v44, v44
	v_cvt_pk_bf16_f32 v4, v54, v55
	v_mfma_f32_16x16x32_bf16 v[102:105], v[30:33], v[124:127], v[102:105]
	v_exp_f32_e32 v45, v45
	v_cvt_pk_bf16_f32 v5, v56, v57
	ds_read_b128 v[236:239], v1 offset:53248
	s_waitcnt lgkmcnt(11)
	v_mfma_f32_16x16x32_bf16 v[136:139], v[34:37], v[174:177], v[148:151]
	v_exp_f32_e32 v46, v46
	s_nop 0
	v_exp_f32_e32 v47, v47
	v_mfma_f32_16x16x32_bf16 v[140:143], v[30:33], v[174:177], v[152:155]
	ds_read_b128 v[148:151], v115 offset:53248
	s_waitcnt lgkmcnt(10)
	v_mfma_f32_16x16x32_bf16 v[128:131], v[34:37], v[158:161], v[212:215]
	v_exp_f32_e32 v48, v48
	v_mfma_f32_16x16x32_bf16 v[132:135], v[30:33], v[158:161], v[208:211]
	v_exp_f32_e32 v49, v49
	ds_read_b128 v[152:155], v1 offset:55296
	s_waitcnt lgkmcnt(9)
	v_mfma_f32_16x16x32_bf16 v[120:123], v[34:37], v[216:219], v[220:223]
	v_exp_f32_e32 v50, v50
	v_mfma_f32_16x16x32_bf16 v[124:127], v[30:33], v[216:219], v[162:165]
	v_exp_f32_e32 v51, v51
	ds_read_b128 v[158:161], v115 offset:55296
	s_waitcnt lgkmcnt(8)
	v_mfma_f32_16x16x32_bf16 v[106:109], v[34:37], v[224:227], v[106:109]
	v_exp_f32_e32 v52, v52
	v_mfma_f32_16x16x32_bf16 v[110:113], v[30:33], v[224:227], v[166:169]
	v_exp_f32_e32 v53, v53
	v_cvt_pk_bf16_f32 v34, v38, v39
	v_cvt_pk_bf16_f32 v35, v40, v41
	v_cvt_pk_bf16_f32 v36, v46, v47
	v_cvt_pk_bf16_f32 v37, v48, v49
	v_cvt_pk_bf16_f32 v30, v42, v43
	v_cvt_pk_bf16_f32 v31, v44, v45
	v_cvt_pk_bf16_f32 v32, v50, v51
	v_cvt_pk_bf16_f32 v33, v52, v53
	s_waitcnt vmcnt(4)
	s_barrier
	ds_read_b64_tr_b16 v[162:163], v203 offset:32768
	ds_read_b64_tr_b16 v[164:165], v203 offset:34816
	s_waitcnt lgkmcnt(9)
	v_mfma_f32_16x16x32_bf16 v[38:41], v[144:147], v[10:13], 0
	s_waitcnt lgkmcnt(8)
	v_mfma_f32_16x16x32_bf16 v[116:119], v[170:173], v[14:17], v[38:41]
	ds_read_b64_tr_b16 v[166:167], v204 offset:32768
	ds_read_b64_tr_b16 v[168:169], v204 offset:34816
	v_mfma_f32_16x16x32_bf16 v[38:41], v[144:147], v[18:21], 0
	v_mfma_f32_16x16x32_bf16 v[58:61], v[170:173], v[22:25], v[38:41]
	ds_read_b64_tr_b16 v[144:145], v205 offset:32768
	ds_read_b64_tr_b16 v[146:147], v205 offset:34816
	s_waitcnt lgkmcnt(11)
	v_mfma_f32_16x16x32_bf16 v[38:41], v[228:231], v[10:13], 0
	s_waitcnt lgkmcnt(10)
	v_mfma_f32_16x16x32_bf16 v[86:89], v[232:235], v[14:17], v[38:41]
	ds_read_b64_tr_b16 v[170:171], v206 offset:32768
	ds_read_b64_tr_b16 v[172:173], v206 offset:34816
	v_mfma_f32_16x16x32_bf16 v[38:41], v[228:231], v[18:21], 0
	v_mfma_f32_16x16x32_bf16 v[54:57], v[232:235], v[22:25], v[38:41]
	ds_read_b64_tr_b16 v[174:175], v203 offset:40960
	ds_read_b64_tr_b16 v[176:177], v203 offset:43008
	s_waitcnt lgkmcnt(13)
	v_mfma_f32_16x16x32_bf16 v[38:41], v[236:239], v[10:13], 0
	s_waitcnt lgkmcnt(12)
	v_mfma_f32_16x16x32_bf16 v[38:41], v[148:151], v[14:17], v[38:41]
	ds_read_b64_tr_b16 v[208:209], v204 offset:40960
	ds_read_b64_tr_b16 v[210:211], v204 offset:43008
	v_mfma_f32_16x16x32_bf16 v[42:45], v[236:239], v[18:21], 0
	v_mfma_f32_16x16x32_bf16 v[42:45], v[148:151], v[22:25], v[42:45]
	ds_read_b64_tr_b16 v[148:149], v205 offset:40960
	ds_read_b64_tr_b16 v[150:151], v205 offset:43008
	s_waitcnt lgkmcnt(14)
	v_mfma_f32_16x16x32_bf16 v[46:49], v[152:155], v[10:13], 0
	v_mfma_f32_16x16x32_bf16 v[46:49], v[158:161], v[14:17], v[46:49]
	ds_read_b64_tr_b16 v[212:213], v206 offset:40960
	ds_read_b64_tr_b16 v[214:215], v206 offset:43008
	v_mfma_f32_16x16x32_bf16 v[50:53], v[152:155], v[18:21], 0
	v_mfma_f32_16x16x32_bf16 v[50:53], v[158:161], v[22:25], v[50:53]
	s_add_u32 s74, s14, 0xfd000000
	s_addc_u32 s75, s15, -1
	s_mov_b32 s76, m0
	s_mov_b32 m0, s52
	s_nop 0
	global_load_lds_dwordx4 v157, s[74:75]
	s_mov_b32 m0, s76
	s_add_u32 s74, s14, 0xfd000080
	s_addc_u32 s75, s15, -1
	s_mov_b32 s76, m0
	s_mov_b32 m0, s53
	s_nop 0
	global_load_lds_dwordx4 v157, s[74:75]
	s_mov_b32 m0, s76
	s_add_u32 s74, s14, 0xffff0000
	s_addc_u32 s75, s15, -1
	s_mov_b32 s76, m0
	s_mov_b32 m0, s62
	s_nop 0
	global_load_lds_dwordx4 v156, s[74:75]
	s_mov_b32 m0, s76
	s_add_u32 s74, s14, 0xffff0080
	s_addc_u32 s75, s15, -1
	s_mov_b32 s76, m0
	s_mov_b32 m0, s63
	s_nop 0
	global_load_lds_dwordx4 v156, s[74:75]
	s_mov_b32 m0, s76
	ds_read_b64_tr_b16 v[152:153], v203 offset:36864
	ds_read_b64_tr_b16 v[154:155], v203 offset:38912
	v_mfma_f32_16x16x32_bf16 v[66:69], v[6:9], v[26:29], v[66:69]
	v_exp_f32_e32 v116, v116
	s_waitcnt lgkmcnt(14)
	v_mfma_f32_16x16x32_bf16 v[62:65], v[6:9], v[162:165], v[62:65]
	v_mfma_f32_16x16x32_bf16 v[70:73], v[2:5], v[26:29], v[70:73]
	v_exp_f32_e32 v117, v117
	v_mfma_f32_16x16x32_bf16 v[78:81], v[2:5], v[162:165], v[78:81]
	ds_read_b64_tr_b16 v[158:159], v204 offset:36864
	ds_read_b64_tr_b16 v[160:161], v204 offset:38912
	v_mfma_f32_16x16x32_bf16 v[74:77], v[6:9], v[166:169], v[74:77]
	v_exp_f32_e32 v118, v118
	v_mfma_f32_16x16x32_bf16 v[82:85], v[2:5], v[166:169], v[82:85]
	v_exp_f32_e32 v119, v119
	ds_read_b64_tr_b16 v[162:163], v205 offset:36864
	ds_read_b64_tr_b16 v[164:165], v205 offset:38912
	s_waitcnt lgkmcnt(14)
	v_mfma_f32_16x16x32_bf16 v[90:93], v[6:9], v[144:147], v[90:93]
	v_exp_f32_e32 v58, v58
	v_mfma_f32_16x16x32_bf16 v[94:97], v[2:5], v[144:147], v[94:97]
	v_exp_f32_e32 v59, v59
	ds_read_b64_tr_b16 v[144:145], v206 offset:36864
	ds_read_b64_tr_b16 v[146:147], v206 offset:38912
	v_mfma_f32_16x16x32_bf16 v[98:101], v[6:9], v[170:173], v[98:101]
	v_exp_f32_e32 v60, v60
	v_mfma_f32_16x16x32_bf16 v[102:105], v[2:5], v[170:173], v[102:105]
	v_exp_f32_e32 v61, v61
	ds_read_b64_tr_b16 v[166:167], v203 offset:45056
	ds_read_b64_tr_b16 v[168:169], v203 offset:47104
	s_waitcnt lgkmcnt(14)
	v_mfma_f32_16x16x32_bf16 v[136:139], v[6:9], v[174:177], v[136:139]
	v_exp_f32_e32 v86, v86
	s_nop 0
	v_exp_f32_e32 v87, v87
	v_mfma_f32_16x16x32_bf16 v[140:143], v[2:5], v[174:177], v[140:143]
	ds_read_b64_tr_b16 v[170:171], v204 offset:45056
	ds_read_b64_tr_b16 v[172:173], v204 offset:47104
	v_exp_f32_e32 v88, v88
	v_mfma_f32_16x16x32_bf16 v[174:177], v[6:9], v[208:211], v[128:131]
	v_mfma_f32_16x16x32_bf16 v[132:135], v[2:5], v[208:211], v[132:135]
	v_exp_f32_e32 v89, v89
	ds_read_b64_tr_b16 v[208:209], v205 offset:45056
	ds_read_b64_tr_b16 v[210:211], v205 offset:47104
	v_exp_f32_e32 v54, v54
	s_waitcnt lgkmcnt(14)
	v_mfma_f32_16x16x32_bf16 v[216:219], v[6:9], v[148:151], v[120:123]
	s_nop 0
	v_exp_f32_e32 v55, v55
	v_mfma_f32_16x16x32_bf16 v[148:151], v[2:5], v[148:151], v[124:127]
	ds_read_b64_tr_b16 v[220:221], v206 offset:45056
	ds_read_b64_tr_b16 v[222:223], v206 offset:47104
	v_exp_f32_e32 v56, v56
	v_mfma_f32_16x16x32_bf16 v[224:227], v[6:9], v[212:215], v[106:109]
	s_nop 0
	v_exp_f32_e32 v57, v57
	v_mfma_f32_16x16x32_bf16 v[212:215], v[2:5], v[212:215], v[110:113]
	ds_read_b128 v[128:131], v1
	v_mfma_f32_16x16x32_bf16 v[66:69], v[34:37], v[26:29], v[66:69]
	v_exp_f32_e32 v38, v38
	v_cvt_pk_bf16_f32 v6, v116, v117
	s_waitcnt lgkmcnt(14)
	v_mfma_f32_16x16x32_bf16 v[62:65], v[34:37], v[152:155], v[62:65]
	v_mfma_f32_16x16x32_bf16 v[70:73], v[30:33], v[26:29], v[70:73]
	v_exp_f32_e32 v39, v39
	v_cvt_pk_bf16_f32 v7, v118, v119
	v_mfma_f32_16x16x32_bf16 v[78:81], v[30:33], v[152:155], v[78:81]
	ds_read_b128 v[152:155], v115
	s_waitcnt lgkmcnt(14)
	v_mfma_f32_16x16x32_bf16 v[74:77], v[34:37], v[158:161], v[74:77]
	v_exp_f32_e32 v40, v40
	v_cvt_pk_bf16_f32 v8, v86, v87
	v_mfma_f32_16x16x32_bf16 v[82:85], v[30:33], v[158:161], v[82:85]
	v_exp_f32_e32 v41, v41
	v_cvt_pk_bf16_f32 v9, v88, v89
	ds_read_b128 v[158:161], v1 offset:2048
	s_waitcnt lgkmcnt(13)
	v_mfma_f32_16x16x32_bf16 v[86:89], v[34:37], v[162:165], v[90:93]
	v_exp_f32_e32 v42, v42
	v_cvt_pk_bf16_f32 v2, v58, v59
	v_mfma_f32_16x16x32_bf16 v[90:93], v[30:33], v[162:165], v[94:97]
	v_exp_f32_e32 v43, v43
	v_cvt_pk_bf16_f32 v3, v60, v61
	ds_read_b128 v[162:165], v115 offset:2048
	s_waitcnt lgkmcnt(12)
	v_mfma_f32_16x16x32_bf16 v[58:61], v[34:37], v[144:147], v[98:101]
	v_exp_f32_e32 v44, v44
	v_cvt_pk_bf16_f32 v4, v54, v55
	v_mfma_f32_16x16x32_bf16 v[94:97], v[30:33], v[144:147], v[102:105]
	v_exp_f32_e32 v45, v45
	v_cvt_pk_bf16_f32 v5, v56, v57
	ds_read_b128 v[144:147], v1 offset:4096
	s_waitcnt lgkmcnt(11)
	v_mfma_f32_16x16x32_bf16 v[120:123], v[34:37], v[166:169], v[136:139]
	v_exp_f32_e32 v46, v46
	v_mfma_f32_16x16x32_bf16 v[124:127], v[30:33], v[166:169], v[140:143]
	v_exp_f32_e32 v47, v47
	ds_read_b128 v[136:139], v115 offset:4096
	s_waitcnt lgkmcnt(10)
	v_mfma_f32_16x16x32_bf16 v[110:113], v[34:37], v[170:173], v[174:177]
	v_exp_f32_e32 v48, v48
	v_mfma_f32_16x16x32_bf16 v[116:119], v[30:33], v[170:173], v[132:135]
	v_exp_f32_e32 v49, v49
	s_nop 1
	ds_read_b128 v[132:135], v1 offset:6144
	s_waitcnt lgkmcnt(9)
	v_mfma_f32_16x16x32_bf16 v[102:105], v[34:37], v[208:211], v[216:219]
	v_exp_f32_e32 v50, v50
	v_mfma_f32_16x16x32_bf16 v[106:109], v[30:33], v[208:211], v[148:151]
	v_exp_f32_e32 v51, v51
	ds_read_b128 v[166:169], v115 offset:6144
	s_waitcnt lgkmcnt(8)
	v_mfma_f32_16x16x32_bf16 v[54:57], v[34:37], v[220:223], v[224:227]
	v_exp_f32_e32 v52, v52
	v_mfma_f32_16x16x32_bf16 v[98:101], v[30:33], v[220:223], v[212:215]
	v_exp_f32_e32 v53, v53
	v_cvt_pk_bf16_f32 v34, v38, v39
	v_cvt_pk_bf16_f32 v35, v40, v41
	v_cvt_pk_bf16_f32 v36, v46, v47
	v_cvt_pk_bf16_f32 v37, v48, v49
	v_cvt_pk_bf16_f32 v30, v42, v43
	v_cvt_pk_bf16_f32 v31, v44, v45
	v_cvt_pk_bf16_f32 v32, v50, v51
	v_cvt_pk_bf16_f32 v33, v52, v53
	s_waitcnt vmcnt(4)
	s_barrier
	ds_read_b64_tr_b16 v[170:171], v203 offset:49152
	ds_read_b64_tr_b16 v[172:173], v203 offset:51200
	s_waitcnt lgkmcnt(9)
	v_mfma_f32_16x16x32_bf16 v[38:41], v[128:131], v[10:13], 0
	s_waitcnt lgkmcnt(8)
	v_mfma_f32_16x16x32_bf16 v[50:53], v[152:155], v[14:17], v[38:41]
	ds_read_b64_tr_b16 v[174:175], v204 offset:49152
	ds_read_b64_tr_b16 v[176:177], v204 offset:51200
	v_mfma_f32_16x16x32_bf16 v[38:41], v[128:131], v[18:21], 0
	v_mfma_f32_16x16x32_bf16 v[42:45], v[152:155], v[22:25], v[38:41]
	ds_read_b64_tr_b16 v[128:129], v205 offset:49152
	ds_read_b64_tr_b16 v[130:131], v205 offset:51200
	s_waitcnt lgkmcnt(11)
	v_mfma_f32_16x16x32_bf16 v[38:41], v[158:161], v[10:13], 0
	s_waitcnt lgkmcnt(10)
	v_mfma_f32_16x16x32_bf16 v[46:49], v[162:165], v[14:17], v[38:41]
	ds_read_b64_tr_b16 v[208:209], v206 offset:49152
	ds_read_b64_tr_b16 v[210:211], v206 offset:51200
	v_mfma_f32_16x16x32_bf16 v[38:41], v[158:161], v[18:21], 0
	v_mfma_f32_16x16x32_bf16 v[38:41], v[162:165], v[22:25], v[38:41]
	ds_read_b64_tr_b16 v[158:159], v203 offset:57344
	ds_read_b64_tr_b16 v[160:161], v203 offset:59392
	s_waitcnt lgkmcnt(13)
	v_mfma_f32_16x16x32_bf16 v[140:143], v[144:147], v[10:13], 0
	s_waitcnt lgkmcnt(12)
	v_mfma_f32_16x16x32_bf16 v[140:143], v[136:139], v[14:17], v[140:143]
	ds_read_b64_tr_b16 v[162:163], v204 offset:57344
	ds_read_b64_tr_b16 v[164:165], v204 offset:59392
	v_mfma_f32_16x16x32_bf16 v[144:147], v[144:147], v[18:21], 0
	v_mfma_f32_16x16x32_bf16 v[144:147], v[136:139], v[22:25], v[144:147]
	ds_read_b64_tr_b16 v[136:137], v205 offset:57344
	ds_read_b64_tr_b16 v[138:139], v205 offset:59392
	s_waitcnt lgkmcnt(14)
	v_mfma_f32_16x16x32_bf16 v[148:151], v[132:135], v[10:13], 0
	v_mfma_f32_16x16x32_bf16 v[148:151], v[166:169], v[14:17], v[148:151]
	ds_read_b64_tr_b16 v[212:213], v206 offset:57344
	ds_read_b64_tr_b16 v[214:215], v206 offset:59392
	v_mfma_f32_16x16x32_bf16 v[132:135], v[132:135], v[18:21], 0
	v_mfma_f32_16x16x32_bf16 v[152:155], v[166:169], v[22:25], v[132:135]
	s_add_u32 s74, s14, 0xfd010000
	s_addc_u32 s75, s15, -1
	s_mov_b32 s76, m0
	s_mov_b32 m0, s66
	s_nop 0
	global_load_lds_dwordx4 v157, s[74:75]
	s_mov_b32 m0, s76
	s_add_u32 s74, s14, 0xfd010080
	s_addc_u32 s75, s15, -1
	s_mov_b32 s76, m0
	s_mov_b32 m0, s28
	s_nop 0
	global_load_lds_dwordx4 v157, s[74:75]
	s_mov_b32 m0, s76
	s_mov_b32 s74, m0
	s_mov_b32 m0, s29
	s_nop 0
	global_load_lds_dwordx4 v156, s[14:15]
	s_mov_b32 m0, s74
	s_add_u32 s74, s14, 0x80
	s_addc_u32 s75, s15, 0
	s_mov_b32 s76, m0
	s_mov_b32 m0, s67
	s_nop 0
	global_load_lds_dwordx4 v156, s[74:75]
	s_mov_b32 m0, s76
	s_nop 0
	ds_read_b64_tr_b16 v[132:133], v203 offset:53248
	ds_read_b64_tr_b16 v[134:135], v203 offset:55296
	v_mfma_f32_16x16x32_bf16 v[66:69], v[6:9], v[26:29], v[66:69]
	v_exp_f32_e32 v50, v50
	s_waitcnt lgkmcnt(14)
	v_mfma_f32_16x16x32_bf16 v[62:65], v[6:9], v[170:173], v[62:65]
	v_mfma_f32_16x16x32_bf16 v[70:73], v[2:5], v[26:29], v[70:73]
	v_exp_f32_e32 v51, v51
	v_mfma_f32_16x16x32_bf16 v[78:81], v[2:5], v[170:173], v[78:81]
	ds_read_b64_tr_b16 v[166:167], v204 offset:53248
	ds_read_b64_tr_b16 v[168:169], v204 offset:55296
	v_mfma_f32_16x16x32_bf16 v[74:77], v[6:9], v[174:177], v[74:77]
	v_exp_f32_e32 v52, v52
	v_mfma_f32_16x16x32_bf16 v[82:85], v[2:5], v[174:177], v[82:85]
	v_exp_f32_e32 v53, v53
	ds_read_b64_tr_b16 v[170:171], v205 offset:53248
	ds_read_b64_tr_b16 v[172:173], v205 offset:55296
	s_waitcnt lgkmcnt(14)
; #define ATT_WAIT_BARV(N) asm volatile("s_waitcnt vmcnt(" #N ")\n\ts_barrier" ::: "memory")
; __device__ __forceinline__ void attn_unit_d16(const UnitDesc& U, char* shm, float lam, const float* subw) {
;     ...
;     for (int t = 1; t <= NT - 4; t += 4) {
;         STEP_D16(t, true, true, true, 1, 2, 0, 0, 3);     ATT_WAIT_BARV(4);
;         STEP_D16(t + 1, true, true, true, 2, 3, 1, 1, 0); ATT_WAIT_BARV(4);
;         STEP_D16(t + 2, true, true, true, 3, 0, 2, 2, 1); ATT_WAIT_BARV(4);
;         STEP_D16(t + 3, true, true, true, 0, 1, 3, 3, 2); ATT_WAIT_BARV(4);
;     }
	v_mfma_f32_16x16x32_bf16 v[86:89], v[6:9], v[128:131], v[86:89]
	v_exp_f32_e32 v42, v42
	v_mfma_f32_16x16x32_bf16 v[128:131], v[2:5], v[128:131], v[90:93]
	v_exp_f32_e32 v43, v43
	ds_read_b64_tr_b16 v[174:175], v206 offset:53248
	ds_read_b64_tr_b16 v[176:177], v206 offset:55296
	v_mfma_f32_16x16x32_bf16 v[58:61], v[6:9], v[208:211], v[58:61]
	v_exp_f32_e32 v44, v44
	s_nop 0
	v_exp_f32_e32 v45, v45
	v_mfma_f32_16x16x32_bf16 v[208:211], v[2:5], v[208:211], v[94:97]
	ds_read_b64_tr_b16 v[216:217], v203 offset:61440
	ds_read_b64_tr_b16 v[218:219], v203 offset:63488
	v_exp_f32_e32 v46, v46
	s_waitcnt lgkmcnt(14)
	v_mfma_f32_16x16x32_bf16 v[220:223], v[6:9], v[158:161], v[120:123]
	s_nop 0
	v_exp_f32_e32 v47, v47
	v_mfma_f32_16x16x32_bf16 v[158:161], v[2:5], v[158:161], v[124:127]
	ds_read_b64_tr_b16 v[224:225], v204 offset:61440
	ds_read_b64_tr_b16 v[226:227], v204 offset:63488
	v_exp_f32_e32 v48, v48
	v_mfma_f32_16x16x32_bf16 v[228:231], v[6:9], v[162:165], v[110:113]
	s_nop 0
	v_exp_f32_e32 v49, v49
	v_mfma_f32_16x16x32_bf16 v[162:165], v[2:5], v[162:165], v[116:119]
	ds_read_b64_tr_b16 v[232:233], v205 offset:61440
	ds_read_b64_tr_b16 v[234:235], v205 offset:63488
	v_exp_f32_e32 v38, v38
	s_waitcnt lgkmcnt(14)
	v_mfma_f32_16x16x32_bf16 v[236:239], v[6:9], v[136:139], v[102:105]
	v_mfma_f32_16x16x32_bf16 v[136:139], v[2:5], v[136:139], v[106:109]
	v_exp_f32_e32 v39, v39
	ds_read_b64_tr_b16 v[240:241], v206 offset:61440
	ds_read_b64_tr_b16 v[242:243], v206 offset:63488
	v_exp_f32_e32 v40, v40
	v_mfma_f32_16x16x32_bf16 v[244:247], v[6:9], v[212:215], v[54:57]
	s_nop 0
	v_exp_f32_e32 v41, v41
	v_mfma_f32_16x16x32_bf16 v[212:215], v[2:5], v[212:215], v[98:101]
	ds_read_b128 v[110:113], v1 offset:16384
	v_mfma_f32_16x16x32_bf16 v[106:109], v[34:37], v[26:29], v[66:69]
	v_exp_f32_e32 v140, v140
	v_cvt_pk_bf16_f32 v6, v50, v51
	s_waitcnt lgkmcnt(14)
	v_mfma_f32_16x16x32_bf16 v[98:101], v[34:37], v[132:135], v[62:65]
	v_mfma_f32_16x16x32_bf16 v[102:105], v[30:33], v[26:29], v[70:73]
	v_exp_f32_e32 v141, v141
	v_cvt_pk_bf16_f32 v7, v52, v53
	v_mfma_f32_16x16x32_bf16 v[90:93], v[30:33], v[132:135], v[78:81]
	ds_read_b128 v[26:29], v115 offset:16384
	s_waitcnt lgkmcnt(14)
	v_mfma_f32_16x16x32_bf16 v[94:97], v[34:37], v[166:169], v[74:77]
	v_exp_f32_e32 v142, v142
	v_cvt_pk_bf16_f32 v8, v46, v47
	v_mfma_f32_16x16x32_bf16 v[82:85], v[30:33], v[166:169], v[82:85]
	v_exp_f32_e32 v143, v143
	v_cvt_pk_bf16_f32 v9, v48, v49
	ds_read_b128 v[116:119], v1 offset:18432
	s_waitcnt lgkmcnt(13)
	v_mfma_f32_16x16x32_bf16 v[86:89], v[34:37], v[170:173], v[86:89]
	v_exp_f32_e32 v144, v144
	v_cvt_pk_bf16_f32 v2, v42, v43
	v_mfma_f32_16x16x32_bf16 v[74:77], v[30:33], v[170:173], v[128:131]
	v_exp_f32_e32 v145, v145
	v_cvt_pk_bf16_f32 v3, v44, v45
	ds_read_b128 v[120:123], v115 offset:18432
	s_waitcnt lgkmcnt(12)
	v_mfma_f32_16x16x32_bf16 v[78:81], v[34:37], v[174:177], v[58:61]
	v_exp_f32_e32 v146, v146
	v_cvt_pk_bf16_f32 v4, v38, v39
	v_mfma_f32_16x16x32_bf16 v[66:69], v[30:33], v[174:177], v[208:211]
	v_exp_f32_e32 v147, v147
	v_cvt_pk_bf16_f32 v5, v40, v41
	ds_read_b128 v[124:127], v1 offset:20480
	s_waitcnt lgkmcnt(11)
	v_mfma_f32_16x16x32_bf16 v[70:73], v[34:37], v[216:219], v[220:223]
	v_exp_f32_e32 v148, v148
	v_mfma_f32_16x16x32_bf16 v[58:61], v[30:33], v[216:219], v[158:161]
	v_exp_f32_e32 v149, v149
	ds_read_b128 v[132:135], v115 offset:20480
	s_waitcnt lgkmcnt(10)
	v_mfma_f32_16x16x32_bf16 v[62:65], v[34:37], v[224:227], v[228:231]
	v_exp_f32_e32 v150, v150
	v_mfma_f32_16x16x32_bf16 v[50:53], v[30:33], v[224:227], v[162:165]
	v_exp_f32_e32 v151, v151
	ds_read_b128 v[128:131], v1 offset:22528
	s_waitcnt lgkmcnt(9)
	v_mfma_f32_16x16x32_bf16 v[54:57], v[34:37], v[232:235], v[236:239]
	v_exp_f32_e32 v152, v152
	v_mfma_f32_16x16x32_bf16 v[42:45], v[30:33], v[232:235], v[136:139]
	v_exp_f32_e32 v153, v153
	s_nop 1
	ds_read_b128 v[136:139], v115 offset:22528
	s_waitcnt lgkmcnt(8)
	v_mfma_f32_16x16x32_bf16 v[46:49], v[34:37], v[240:243], v[244:247]
	v_exp_f32_e32 v154, v154
	v_mfma_f32_16x16x32_bf16 v[38:41], v[30:33], v[240:243], v[212:215]
	v_exp_f32_e32 v155, v155
	v_cvt_pk_bf16_f32 v34, v140, v141
	v_cvt_pk_bf16_f32 v35, v142, v143
	v_cvt_pk_bf16_f32 v36, v148, v149
	v_cvt_pk_bf16_f32 v37, v150, v151
	v_cvt_pk_bf16_f32 v30, v144, v145
	v_cvt_pk_bf16_f32 v31, v146, v147
	v_cvt_pk_bf16_f32 v32, v152, v153
	v_cvt_pk_bf16_f32 v33, v154, v155
	s_add_i32 s33, s33, 4
	s_add_u32 s14, s14, 0x40000
	s_waitcnt vmcnt(4)
	s_barrier
	s_addc_u32 s15, s15, 0
	s_cmpk_gt_u32 s33, 0x78
	s_cbranch_scc0 .LBB0_444
; #define ATT_WAIT_BAR(N) asm volatile("s_waitcnt vmcnt(" #N ") lgkmcnt(0)\n\ts_barrier" ::: "memory")
; __device__ __forceinline__ void attn_unit_d16(const UnitDesc& U, char* shm, float lam, const float* subw) {
;     ...
;     STEP_D16(NT - 3, false, true, true, 1, 2, 0, 0, 3);   ATT_WAIT_BAR(2);
	ds_read_b64_tr_b16 v[158:159], v203
	ds_read_b64_tr_b16 v[160:161], v203 offset:2048
	s_waitcnt lgkmcnt(9)
	v_mfma_f32_16x16x32_bf16 v[140:143], v[110:113], v[10:13], 0
	s_waitcnt lgkmcnt(8)
	v_mfma_f32_16x16x32_bf16 v[152:155], v[26:29], v[14:17], v[140:143]
	ds_read_b64_tr_b16 v[162:163], v204
	ds_read_b64_tr_b16 v[164:165], v204 offset:2048
	v_mfma_f32_16x16x32_bf16 v[110:113], v[110:113], v[18:21], 0
	v_mfma_f32_16x16x32_bf16 v[144:147], v[26:29], v[22:25], v[110:113]
	ds_read_b64_tr_b16 v[166:167], v205
	ds_read_b64_tr_b16 v[168:169], v205 offset:2048
	s_waitcnt lgkmcnt(11)
	v_mfma_f32_16x16x32_bf16 v[26:29], v[116:119], v[10:13], 0
	s_waitcnt lgkmcnt(10)
	v_mfma_f32_16x16x32_bf16 v[148:151], v[120:123], v[14:17], v[26:29]
	ds_read_b64_tr_b16 v[170:171], v206
	ds_read_b64_tr_b16 v[172:173], v206 offset:2048
	v_mfma_f32_16x16x32_bf16 v[26:29], v[116:119], v[18:21], 0
	v_mfma_f32_16x16x32_bf16 v[140:143], v[120:123], v[22:25], v[26:29]
	ds_read_b64_tr_b16 v[174:175], v203 offset:8192
	ds_read_b64_tr_b16 v[176:177], v203 offset:10240
	s_waitcnt lgkmcnt(13)
	v_mfma_f32_16x16x32_bf16 v[26:29], v[124:127], v[10:13], 0
	s_waitcnt lgkmcnt(12)
	v_mfma_f32_16x16x32_bf16 v[110:113], v[132:135], v[14:17], v[26:29]
	ds_read_b64_tr_b16 v[208:209], v204 offset:8192
	ds_read_b64_tr_b16 v[210:211], v204 offset:10240
	v_mfma_f32_16x16x32_bf16 v[26:29], v[124:127], v[18:21], 0
	v_mfma_f32_16x16x32_bf16 v[116:119], v[132:135], v[22:25], v[26:29]
	ds_read_b64_tr_b16 v[132:133], v205 offset:8192
	ds_read_b64_tr_b16 v[134:135], v205 offset:10240
	s_waitcnt lgkmcnt(14)
	v_mfma_f32_16x16x32_bf16 v[26:29], v[128:131], v[10:13], 0
	v_mfma_f32_16x16x32_bf16 v[120:123], v[136:139], v[14:17], v[26:29]
	ds_read_b64_tr_b16 v[212:213], v206 offset:8192
	ds_read_b64_tr_b16 v[214:215], v206 offset:10240
	v_mfma_f32_16x16x32_bf16 v[26:29], v[128:131], v[18:21], 0
	v_mfma_f32_16x16x32_bf16 v[124:127], v[136:139], v[22:25], v[26:29]
	s_add_u32 s14, s10, 0x7f0000
	s_addc_u32 s15, s11, 0
	s_mov_b32 s28, m0
	s_mov_b32 m0, s68
	s_nop 0
	global_load_lds_dwordx4 v156, s[14:15]
	s_mov_b32 m0, s28
	s_add_u32 s10, s10, 0x7f0080
	s_addc_u32 s11, s11, 0
	s_mov_b32 s14, m0
	s_mov_b32 m0, s69
	s_nop 0
	global_load_lds_dwordx4 v156, s[10:11]
	s_mov_b32 m0, s14
	ds_read_b64_tr_b16 v[128:129], v203 offset:4096
	ds_read_b64_tr_b16 v[130:131], v203 offset:6144
	s_nop 0
	v_mov_b64_e32 v[28:29], v[250:251]
	v_mov_b64_e32 v[26:27], v[248:249]
	v_exp_f32_e32 v152, v152
	s_waitcnt lgkmcnt(14)
	v_mfma_f32_16x16x32_bf16 v[98:101], v[6:9], v[158:161], v[98:101]
	v_mfma_f32_16x16x32_bf16 v[106:109], v[6:9], v[26:29], v[106:109]
	v_exp_f32_e32 v153, v153
	v_mfma_f32_16x16x32_bf16 v[102:105], v[2:5], v[26:29], v[102:105]
	v_mfma_f32_16x16x32_bf16 v[90:93], v[2:5], v[158:161], v[90:93]
	ds_read_b64_tr_b16 v[136:137], v204 offset:4096
	ds_read_b64_tr_b16 v[138:139], v204 offset:6144
	v_exp_f32_e32 v154, v154
	v_mfma_f32_16x16x32_bf16 v[94:97], v[6:9], v[162:165], v[94:97]
	v_mfma_f32_16x16x32_bf16 v[82:85], v[2:5], v[162:165], v[82:85]
	v_exp_f32_e32 v155, v155
	ds_read_b64_tr_b16 v[156:157], v205 offset:4096
	ds_read_b64_tr_b16 v[158:159], v205 offset:6144
	v_exp_f32_e32 v144, v144
	s_waitcnt lgkmcnt(14)
	v_mfma_f32_16x16x32_bf16 v[86:89], v[6:9], v[166:169], v[86:89]
	s_nop 0
	v_exp_f32_e32 v145, v145
	v_mfma_f32_16x16x32_bf16 v[160:163], v[2:5], v[166:169], v[74:77]
	ds_read_b64_tr_b16 v[164:165], v206 offset:4096
	ds_read_b64_tr_b16 v[166:167], v206 offset:6144
	v_exp_f32_e32 v146, v146
	v_mfma_f32_16x16x32_bf16 v[216:219], v[6:9], v[170:173], v[78:81]
	s_nop 0
	v_exp_f32_e32 v147, v147
	v_mfma_f32_16x16x32_bf16 v[168:171], v[2:5], v[170:173], v[66:69]
	ds_read_b64_tr_b16 v[220:221], v203 offset:12288
	ds_read_b64_tr_b16 v[222:223], v203 offset:14336
	v_exp_f32_e32 v148, v148
	s_waitcnt lgkmcnt(14)
	v_mfma_f32_16x16x32_bf16 v[224:227], v[6:9], v[174:177], v[70:73]
	v_mfma_f32_16x16x32_bf16 v[58:61], v[2:5], v[174:177], v[58:61]
	v_exp_f32_e32 v149, v149
	ds_read_b64_tr_b16 v[172:173], v204 offset:12288
	ds_read_b64_tr_b16 v[174:175], v204 offset:14336
	v_exp_f32_e32 v150, v150
	v_mfma_f32_16x16x32_bf16 v[176:179], v[6:9], v[208:211], v[62:65]
	v_mfma_f32_16x16x32_bf16 v[50:53], v[2:5], v[208:211], v[50:53]
	v_exp_f32_e32 v151, v151
	ds_read_b64_tr_b16 v[208:209], v205 offset:12288
	ds_read_b64_tr_b16 v[210:211], v205 offset:14336
	s_waitcnt lgkmcnt(14)
	v_mfma_f32_16x16x32_bf16 v[54:57], v[6:9], v[132:135], v[54:57]
	v_exp_f32_e32 v140, v140
	v_mfma_f32_16x16x32_bf16 v[42:45], v[2:5], v[132:135], v[42:45]
	v_exp_f32_e32 v141, v141
	ds_read_b64_tr_b16 v[228:229], v206 offset:12288
	ds_read_b64_tr_b16 v[230:231], v206 offset:14336
	v_mfma_f32_16x16x32_bf16 v[46:49], v[6:9], v[212:215], v[46:49]
	v_exp_f32_e32 v142, v142
	s_nop 0
	v_exp_f32_e32 v143, v143
	v_mfma_f32_16x16x32_bf16 v[212:215], v[2:5], v[212:215], v[38:41]
	s_nop 2
	ds_read_b128 v[38:41], v1 offset:32768
	v_mfma_f32_16x16x32_bf16 v[66:69], v[34:37], v[26:29], v[106:109]
	v_exp_f32_e32 v110, v110
	v_cvt_pk_bf16_f32 v6, v152, v153
	s_waitcnt lgkmcnt(14)
	v_mfma_f32_16x16x32_bf16 v[62:65], v[34:37], v[128:131], v[98:101]
	v_mfma_f32_16x16x32_bf16 v[70:73], v[30:33], v[26:29], v[102:105]
	v_exp_f32_e32 v111, v111
	v_cvt_pk_bf16_f32 v7, v154, v155
	v_mfma_f32_16x16x32_bf16 v[78:81], v[30:33], v[128:131], v[90:93]
	ds_read_b128 v[232:235], v115 offset:32768
	s_waitcnt lgkmcnt(14)
	v_mfma_f32_16x16x32_bf16 v[74:77], v[34:37], v[136:139], v[94:97]
	v_exp_f32_e32 v112, v112
	v_cvt_pk_bf16_f32 v8, v148, v149
	v_mfma_f32_16x16x32_bf16 v[82:85], v[30:33], v[136:139], v[82:85]
	v_exp_f32_e32 v113, v113
	v_cvt_pk_bf16_f32 v9, v150, v151
	ds_read_b128 v[236:239], v1 offset:34816
	v_exp_f32_e32 v116, v116
	v_cvt_pk_bf16_f32 v2, v144, v145
	s_waitcnt lgkmcnt(13)
; #define ATT_WAIT_BAR(N) asm volatile("s_waitcnt vmcnt(" #N ") lgkmcnt(0)\n\ts_barrier" ::: "memory")
; __device__ __forceinline__ void attn_unit_d16(const UnitDesc& U, char* shm, float lam, const float* subw) {
;     ...
;     STEP_D16(NT - 2, false, false, true, 2, 3, 1, 1, 0);  ATT_WAIT_BAR(0);
	v_mfma_f32_16x16x32_bf16 v[90:93], v[34:37], v[156:159], v[86:89]
	s_nop 0
	v_exp_f32_e32 v117, v117
	v_cvt_pk_bf16_f32 v3, v146, v147
	v_mfma_f32_16x16x32_bf16 v[94:97], v[30:33], v[156:159], v[160:163]
	ds_read_b128 v[156:159], v115 offset:34816
	v_exp_f32_e32 v118, v118
	v_cvt_pk_bf16_f32 v4, v140, v141
	s_waitcnt lgkmcnt(12)
	v_mfma_f32_16x16x32_bf16 v[98:101], v[34:37], v[164:167], v[216:219]
	s_nop 0
	v_exp_f32_e32 v119, v119
	v_cvt_pk_bf16_f32 v5, v142, v143
	v_mfma_f32_16x16x32_bf16 v[102:105], v[30:33], v[164:167], v[168:171]
	ds_read_b128 v[160:163], v1 offset:36864
	v_exp_f32_e32 v120, v120
	s_waitcnt lgkmcnt(11)
	v_mfma_f32_16x16x32_bf16 v[148:151], v[34:37], v[220:223], v[224:227]
	s_nop 0
	v_exp_f32_e32 v121, v121
	v_mfma_f32_16x16x32_bf16 v[152:155], v[30:33], v[220:223], v[58:61]
	ds_read_b128 v[164:167], v115 offset:36864
	v_exp_f32_e32 v122, v122
	s_waitcnt lgkmcnt(10)
	v_mfma_f32_16x16x32_bf16 v[140:143], v[34:37], v[172:175], v[176:179]
	s_nop 0
	v_exp_f32_e32 v123, v123
	v_mfma_f32_16x16x32_bf16 v[144:147], v[30:33], v[172:175], v[50:53]
	s_nop 2
	ds_read_b128 v[50:53], v1 offset:38912
	v_exp_f32_e32 v124, v124
	s_waitcnt lgkmcnt(9)
	v_mfma_f32_16x16x32_bf16 v[132:135], v[34:37], v[208:211], v[54:57]
	s_nop 0
	v_exp_f32_e32 v125, v125
	v_mfma_f32_16x16x32_bf16 v[136:139], v[30:33], v[208:211], v[42:45]
	ds_read_b128 v[168:171], v115 offset:38912
	v_exp_f32_e32 v126, v126
	s_waitcnt lgkmcnt(8)
	v_mfma_f32_16x16x32_bf16 v[106:109], v[34:37], v[228:231], v[46:49]
	s_nop 0
	v_exp_f32_e32 v127, v127
	v_mfma_f32_16x16x32_bf16 v[128:131], v[30:33], v[228:231], v[212:215]
	v_cvt_pk_bf16_f32 v34, v110, v111
	v_cvt_pk_bf16_f32 v35, v112, v113
	v_cvt_pk_bf16_f32 v36, v120, v121
	v_cvt_pk_bf16_f32 v37, v122, v123
	v_cvt_pk_bf16_f32 v30, v116, v117
	v_cvt_pk_bf16_f32 v31, v118, v119
	v_cvt_pk_bf16_f32 v32, v124, v125
	v_cvt_pk_bf16_f32 v33, v126, v127
	s_waitcnt vmcnt(2) lgkmcnt(0)
	s_barrier
	ds_read_b64_tr_b16 v[116:117], v203 offset:16384
	ds_read_b64_tr_b16 v[118:119], v203 offset:18432
	s_waitcnt lgkmcnt(9)
	v_mfma_f32_16x16x32_bf16 v[42:45], v[38:41], v[10:13], 0
	s_waitcnt lgkmcnt(8)
	v_mfma_f32_16x16x32_bf16 v[110:113], v[232:235], v[14:17], v[42:45]
	ds_read_b64_tr_b16 v[120:121], v204 offset:16384
	ds_read_b64_tr_b16 v[122:123], v204 offset:18432
	v_mfma_f32_16x16x32_bf16 v[38:41], v[38:41], v[18:21], 0
	v_mfma_f32_16x16x32_bf16 v[58:61], v[232:235], v[22:25], v[38:41]
	ds_read_b64_tr_b16 v[124:125], v205 offset:16384
	ds_read_b64_tr_b16 v[126:127], v205 offset:18432
	s_waitcnt lgkmcnt(11)
	v_mfma_f32_16x16x32_bf16 v[38:41], v[236:239], v[10:13], 0
	s_waitcnt lgkmcnt(10)
	v_mfma_f32_16x16x32_bf16 v[86:89], v[156:159], v[14:17], v[38:41]
	ds_read_b64_tr_b16 v[172:173], v206 offset:16384
	ds_read_b64_tr_b16 v[174:175], v206 offset:18432
	v_mfma_f32_16x16x32_bf16 v[38:41], v[236:239], v[18:21], 0
	v_mfma_f32_16x16x32_bf16 v[54:57], v[156:159], v[22:25], v[38:41]
	ds_read_b64_tr_b16 v[156:157], v203 offset:24576
	ds_read_b64_tr_b16 v[158:159], v203 offset:26624
	s_waitcnt lgkmcnt(13)
	v_mfma_f32_16x16x32_bf16 v[38:41], v[160:163], v[10:13], 0
	s_waitcnt lgkmcnt(12)
	v_mfma_f32_16x16x32_bf16 v[38:41], v[164:167], v[14:17], v[38:41]
	ds_read_b64_tr_b16 v[176:177], v204 offset:24576
	ds_read_b64_tr_b16 v[178:179], v204 offset:26624
	v_mfma_f32_16x16x32_bf16 v[42:45], v[160:163], v[18:21], 0
	v_mfma_f32_16x16x32_bf16 v[42:45], v[164:167], v[22:25], v[42:45]
	ds_read_b64_tr_b16 v[160:161], v205 offset:24576
	ds_read_b64_tr_b16 v[162:163], v205 offset:26624
	s_waitcnt lgkmcnt(14)
	v_mfma_f32_16x16x32_bf16 v[46:49], v[50:53], v[10:13], 0
	v_mfma_f32_16x16x32_bf16 v[46:49], v[168:171], v[14:17], v[46:49]
	ds_read_b64_tr_b16 v[164:165], v206 offset:24576
	ds_read_b64_tr_b16 v[166:167], v206 offset:26624
	v_mfma_f32_16x16x32_bf16 v[50:53], v[50:53], v[18:21], 0
	v_mfma_f32_16x16x32_bf16 v[50:53], v[168:171], v[22:25], v[50:53]
	ds_read_b64_tr_b16 v[168:169], v203 offset:20480
	ds_read_b64_tr_b16 v[170:171], v203 offset:22528
	v_mfma_f32_16x16x32_bf16 v[66:69], v[6:9], v[26:29], v[66:69]
	v_exp_f32_e32 v110, v110
	s_waitcnt lgkmcnt(14)
	v_mfma_f32_16x16x32_bf16 v[62:65], v[6:9], v[116:119], v[62:65]
	v_mfma_f32_16x16x32_bf16 v[70:73], v[2:5], v[26:29], v[70:73]
	v_exp_f32_e32 v111, v111
	v_mfma_f32_16x16x32_bf16 v[78:81], v[2:5], v[116:119], v[78:81]
	ds_read_b64_tr_b16 v[116:117], v204 offset:20480
	ds_read_b64_tr_b16 v[118:119], v204 offset:22528
	v_mfma_f32_16x16x32_bf16 v[74:77], v[6:9], v[120:123], v[74:77]
	v_exp_f32_e32 v112, v112
	v_mfma_f32_16x16x32_bf16 v[82:85], v[2:5], v[120:123], v[82:85]
	v_exp_f32_e32 v113, v113
	ds_read_b64_tr_b16 v[120:121], v205 offset:20480
	ds_read_b64_tr_b16 v[122:123], v205 offset:22528
	v_exp_f32_e32 v58, v58
	s_waitcnt lgkmcnt(14)
	v_mfma_f32_16x16x32_bf16 v[90:93], v[6:9], v[124:127], v[90:93]
	s_nop 0
	v_exp_f32_e32 v59, v59
	v_mfma_f32_16x16x32_bf16 v[94:97], v[2:5], v[124:127], v[94:97]
	ds_read_b64_tr_b16 v[124:125], v206 offset:20480
	ds_read_b64_tr_b16 v[126:127], v206 offset:22528
	v_exp_f32_e32 v60, v60
	v_mfma_f32_16x16x32_bf16 v[98:101], v[6:9], v[172:175], v[98:101]
	s_nop 0
	v_exp_f32_e32 v61, v61
	v_mfma_f32_16x16x32_bf16 v[102:105], v[2:5], v[172:175], v[102:105]
	ds_read_b64_tr_b16 v[172:173], v203 offset:28672
	ds_read_b64_tr_b16 v[174:175], v203 offset:30720
	v_exp_f32_e32 v86, v86
	s_waitcnt lgkmcnt(14)
; #define ATT_WAIT_BAR(N) asm volatile("s_waitcnt vmcnt(" #N ") lgkmcnt(0)\n\ts_barrier" ::: "memory")
; __device__ __forceinline__ void attn_unit_d16(const UnitDesc& U, char* shm, float lam, const float* subw) {
;     ...
;     STEP_D16(NT - 1, false, false, false, 3, 0, 2, 2, 1); ATT_WAIT_BAR(0);
	v_mfma_f32_16x16x32_bf16 v[148:151], v[6:9], v[156:159], v[148:151]
	s_nop 0
	v_exp_f32_e32 v87, v87
	v_mfma_f32_16x16x32_bf16 v[152:155], v[2:5], v[156:159], v[152:155]
	ds_read_b64_tr_b16 v[156:157], v204 offset:28672
	ds_read_b64_tr_b16 v[158:159], v204 offset:30720
	v_exp_f32_e32 v88, v88
	v_mfma_f32_16x16x32_bf16 v[140:143], v[6:9], v[176:179], v[140:143]
	s_nop 0
	v_exp_f32_e32 v89, v89
	v_mfma_f32_16x16x32_bf16 v[144:147], v[2:5], v[176:179], v[144:147]
	ds_read_b64_tr_b16 v[176:177], v205 offset:28672
	ds_read_b64_tr_b16 v[178:179], v205 offset:30720
	v_exp_f32_e32 v54, v54
	s_waitcnt lgkmcnt(14)
	v_mfma_f32_16x16x32_bf16 v[208:211], v[6:9], v[160:163], v[132:135]
	s_nop 0
	v_exp_f32_e32 v55, v55
	v_mfma_f32_16x16x32_bf16 v[160:163], v[2:5], v[160:163], v[136:139]
	ds_read_b64_tr_b16 v[212:213], v206 offset:28672
	ds_read_b64_tr_b16 v[214:215], v206 offset:30720
	v_exp_f32_e32 v56, v56
	v_mfma_f32_16x16x32_bf16 v[216:219], v[6:9], v[164:167], v[106:109]
	s_nop 0
	v_exp_f32_e32 v57, v57
	v_mfma_f32_16x16x32_bf16 v[164:167], v[2:5], v[164:167], v[128:131]
	ds_read_b128 v[136:139], v1 offset:49152
	v_mfma_f32_16x16x32_bf16 v[66:69], v[34:37], v[26:29], v[66:69]
	v_exp_f32_e32 v38, v38
	v_cvt_pk_bf16_f32 v6, v110, v111
	s_waitcnt lgkmcnt(14)
	v_mfma_f32_16x16x32_bf16 v[62:65], v[34:37], v[168:171], v[62:65]
	v_mfma_f32_16x16x32_bf16 v[70:73], v[30:33], v[26:29], v[70:73]
	v_exp_f32_e32 v39, v39
	v_cvt_pk_bf16_f32 v7, v112, v113
	v_mfma_f32_16x16x32_bf16 v[78:81], v[30:33], v[168:171], v[78:81]
	ds_read_b128 v[168:171], v115 offset:49152
	s_waitcnt lgkmcnt(14)
	v_mfma_f32_16x16x32_bf16 v[74:77], v[34:37], v[116:119], v[74:77]
	v_exp_f32_e32 v40, v40
	v_cvt_pk_bf16_f32 v8, v86, v87
	v_mfma_f32_16x16x32_bf16 v[82:85], v[30:33], v[116:119], v[82:85]
	v_exp_f32_e32 v41, v41
	v_cvt_pk_bf16_f32 v9, v88, v89
	ds_read_b128 v[220:223], v1 offset:51200
	v_exp_f32_e32 v42, v42
	v_cvt_pk_bf16_f32 v2, v58, v59
	s_waitcnt lgkmcnt(13)
	v_mfma_f32_16x16x32_bf16 v[86:89], v[34:37], v[120:123], v[90:93]
	s_nop 0
	v_exp_f32_e32 v43, v43
	v_cvt_pk_bf16_f32 v3, v60, v61
	v_mfma_f32_16x16x32_bf16 v[90:93], v[30:33], v[120:123], v[94:97]
	ds_read_b128 v[224:227], v115 offset:51200
	s_waitcnt lgkmcnt(12)
	v_mfma_f32_16x16x32_bf16 v[58:61], v[34:37], v[124:127], v[98:101]
	v_exp_f32_e32 v44, v44
	v_cvt_pk_bf16_f32 v4, v54, v55
	s_nop 0
	v_exp_f32_e32 v45, v45
	v_cvt_pk_bf16_f32 v5, v56, v57
	v_mfma_f32_16x16x32_bf16 v[94:97], v[30:33], v[124:127], v[102:105]
	ds_read_b128 v[228:231], v1 offset:53248
	v_exp_f32_e32 v46, v46
	s_waitcnt lgkmcnt(11)
	v_mfma_f32_16x16x32_bf16 v[128:131], v[34:37], v[172:175], v[148:151]
	s_nop 0
	v_exp_f32_e32 v47, v47
	v_mfma_f32_16x16x32_bf16 v[132:135], v[30:33], v[172:175], v[152:155]
	ds_read_b128 v[148:151], v115 offset:53248
	v_exp_f32_e32 v48, v48
	s_waitcnt lgkmcnt(10)
	v_mfma_f32_16x16x32_bf16 v[120:123], v[34:37], v[156:159], v[140:143]
	s_nop 0
	v_exp_f32_e32 v49, v49
	v_mfma_f32_16x16x32_bf16 v[124:127], v[30:33], v[156:159], v[144:147]
	ds_read_b128 v[140:143], v1 offset:55296
	v_exp_f32_e32 v50, v50
	s_waitcnt lgkmcnt(9)
	v_mfma_f32_16x16x32_bf16 v[106:109], v[34:37], v[176:179], v[208:211]
	s_nop 0
	v_exp_f32_e32 v51, v51
	v_mfma_f32_16x16x32_bf16 v[110:113], v[30:33], v[176:179], v[160:163]
	ds_read_b128 v[144:147], v115 offset:55296
	v_exp_f32_e32 v52, v52
	s_waitcnt lgkmcnt(8)
	v_mfma_f32_16x16x32_bf16 v[98:101], v[34:37], v[212:215], v[216:219]
	s_nop 0
	v_exp_f32_e32 v53, v53
	v_mfma_f32_16x16x32_bf16 v[102:105], v[30:33], v[212:215], v[164:167]
	v_cvt_pk_bf16_f32 v34, v38, v39
	v_cvt_pk_bf16_f32 v35, v40, v41
	v_cvt_pk_bf16_f32 v36, v46, v47
	v_cvt_pk_bf16_f32 v37, v48, v49
	v_cvt_pk_bf16_f32 v30, v42, v43
	v_cvt_pk_bf16_f32 v31, v44, v45
	v_cvt_pk_bf16_f32 v32, v50, v51
	v_cvt_pk_bf16_f32 v33, v52, v53
	s_waitcnt vmcnt(0) lgkmcnt(0)
	s_barrier
	ds_read_b64_tr_b16 v[152:153], v203 offset:32768
	ds_read_b64_tr_b16 v[154:155], v203 offset:34816
	s_waitcnt lgkmcnt(9)
	v_mfma_f32_16x16x32_bf16 v[38:41], v[136:139], v[10:13], 0
	s_waitcnt lgkmcnt(8)
	v_mfma_f32_16x16x32_bf16 v[116:119], v[168:171], v[14:17], v[38:41]
	ds_read_b64_tr_b16 v[156:157], v204 offset:32768
	ds_read_b64_tr_b16 v[158:159], v204 offset:34816
	v_mfma_f32_16x16x32_bf16 v[38:41], v[136:139], v[18:21], 0
	v_mfma_f32_16x16x32_bf16 v[50:53], v[168:171], v[22:25], v[38:41]
	ds_read_b64_tr_b16 v[136:137], v205 offset:32768
	ds_read_b64_tr_b16 v[138:139], v205 offset:34816
	s_waitcnt lgkmcnt(11)
	v_mfma_f32_16x16x32_bf16 v[38:41], v[220:223], v[10:13], 0
	s_waitcnt lgkmcnt(10)
	v_mfma_f32_16x16x32_bf16 v[54:57], v[224:227], v[14:17], v[38:41]
	ds_read_b64_tr_b16 v[160:161], v206 offset:32768
	ds_read_b64_tr_b16 v[162:163], v206 offset:34816
	v_mfma_f32_16x16x32_bf16 v[38:41], v[220:223], v[18:21], 0
	v_mfma_f32_16x16x32_bf16 v[46:49], v[224:227], v[22:25], v[38:41]
	ds_read_b64_tr_b16 v[164:165], v203 offset:40960
	ds_read_b64_tr_b16 v[166:167], v203 offset:43008
	s_waitcnt lgkmcnt(13)
	v_mfma_f32_16x16x32_bf16 v[38:41], v[228:231], v[10:13], 0
	s_waitcnt lgkmcnt(12)
	v_mfma_f32_16x16x32_bf16 v[38:41], v[148:151], v[14:17], v[38:41]
	ds_read_b64_tr_b16 v[168:169], v204 offset:40960
	ds_read_b64_tr_b16 v[170:171], v204 offset:43008
	v_mfma_f32_16x16x32_bf16 v[42:45], v[228:231], v[18:21], 0
	v_mfma_f32_16x16x32_bf16 v[42:45], v[148:151], v[22:25], v[42:45]
	ds_read_b64_tr_b16 v[148:149], v205 offset:40960
	ds_read_b64_tr_b16 v[150:151], v205 offset:43008
	s_waitcnt lgkmcnt(14)
	v_mfma_f32_16x16x32_bf16 v[10:13], v[140:143], v[10:13], 0
	v_mfma_f32_16x16x32_bf16 v[10:13], v[144:147], v[14:17], v[10:13]
	ds_read_b64_tr_b16 v[172:173], v206 offset:40960
	ds_read_b64_tr_b16 v[174:175], v206 offset:43008
	v_mfma_f32_16x16x32_bf16 v[14:17], v[140:143], v[18:21], 0
	v_mfma_f32_16x16x32_bf16 v[14:17], v[144:147], v[22:25], v[14:17]
	ds_read_b64_tr_b16 v[140:141], v203 offset:36864
	ds_read_b64_tr_b16 v[142:143], v203 offset:38912
	v_mfma_f32_16x16x32_bf16 v[18:21], v[6:9], v[26:29], v[66:69]
	v_exp_f32_e32 v116, v116
	s_waitcnt lgkmcnt(14)
	v_mfma_f32_16x16x32_bf16 v[22:25], v[6:9], v[152:155], v[62:65]
	v_mfma_f32_16x16x32_bf16 v[62:65], v[2:5], v[26:29], v[70:73]
	v_exp_f32_e32 v117, v117
	v_mfma_f32_16x16x32_bf16 v[66:69], v[2:5], v[152:155], v[78:81]
	s_nop 0
	ds_read_b64_tr_b16 v[70:71], v204 offset:36864
	ds_read_b64_tr_b16 v[72:73], v204 offset:38912
	v_mfma_f32_16x16x32_bf16 v[74:77], v[6:9], v[156:159], v[74:77]
	v_exp_f32_e32 v118, v118
	v_mfma_f32_16x16x32_bf16 v[78:81], v[2:5], v[156:159], v[82:85]
	v_exp_f32_e32 v119, v119
	s_nop 1
	ds_read_b64_tr_b16 v[82:83], v205 offset:36864
	ds_read_b64_tr_b16 v[84:85], v205 offset:38912
	v_exp_f32_e32 v50, v50
	s_waitcnt lgkmcnt(14)
	v_mfma_f32_16x16x32_bf16 v[86:89], v[6:9], v[136:139], v[86:89]
	s_nop 0
	v_exp_f32_e32 v51, v51
	v_mfma_f32_16x16x32_bf16 v[90:93], v[2:5], v[136:139], v[90:93]
	ds_read_b64_tr_b16 v[136:137], v206 offset:36864
	ds_read_b64_tr_b16 v[138:139], v206 offset:38912
	v_exp_f32_e32 v52, v52
	v_mfma_f32_16x16x32_bf16 v[144:147], v[6:9], v[160:163], v[58:61]
	s_nop 0
	v_exp_f32_e32 v53, v53
	v_mfma_f32_16x16x32_bf16 v[94:97], v[2:5], v[160:163], v[94:97]
	ds_read_b64_tr_b16 v[152:153], v203 offset:45056
	ds_read_b64_tr_b16 v[154:155], v203 offset:47104
	v_exp_f32_e32 v54, v54
	s_waitcnt lgkmcnt(14)
	v_mfma_f32_16x16x32_bf16 v[128:131], v[6:9], v[164:167], v[128:131]
	s_nop 0
	v_exp_f32_e32 v55, v55
	v_mfma_f32_16x16x32_bf16 v[132:135], v[2:5], v[164:167], v[132:135]
	ds_read_b64_tr_b16 v[156:157], v204 offset:45056
	ds_read_b64_tr_b16 v[158:159], v204 offset:47104
	v_exp_f32_e32 v56, v56
	v_mfma_f32_16x16x32_bf16 v[120:123], v[6:9], v[168:171], v[120:123]
	s_nop 0
	v_exp_f32_e32 v57, v57
	v_mfma_f32_16x16x32_bf16 v[124:127], v[2:5], v[168:171], v[124:127]
	ds_read_b64_tr_b16 v[160:161], v205 offset:45056
	ds_read_b64_tr_b16 v[162:163], v205 offset:47104
	v_exp_f32_e32 v46, v46
	s_waitcnt lgkmcnt(14)
	v_mfma_f32_16x16x32_bf16 v[106:109], v[6:9], v[148:151], v[106:109]
	s_nop 0
	v_exp_f32_e32 v47, v47
	v_mfma_f32_16x16x32_bf16 v[110:113], v[2:5], v[148:151], v[110:113]
	ds_read_b64_tr_b16 v[148:149], v206 offset:45056
	ds_read_b64_tr_b16 v[150:151], v206 offset:47104
	v_exp_f32_e32 v48, v48
	v_mfma_f32_16x16x32_bf16 v[98:101], v[6:9], v[172:175], v[98:101]
	s_nop 0
	v_exp_f32_e32 v49, v49
	v_mfma_f32_16x16x32_bf16 v[102:105], v[2:5], v[172:175], v[102:105]
	v_mfma_f32_16x16x32_bf16 v[18:21], v[34:37], v[26:29], v[18:21]
	v_exp_f32_e32 v38, v38
	v_cvt_pk_bf16_f32 v6, v116, v117
	s_waitcnt lgkmcnt(14)
	v_mfma_f32_16x16x32_bf16 v[58:61], v[34:37], v[140:143], v[22:25]
	v_mfma_f32_16x16x32_bf16 v[66:69], v[30:33], v[140:143], v[66:69]
	v_exp_f32_e32 v39, v39
	v_cvt_pk_bf16_f32 v7, v118, v119
	v_mfma_f32_16x16x32_bf16 v[22:25], v[30:33], v[26:29], v[62:65]
	s_waitcnt lgkmcnt(12)
	v_mfma_f32_16x16x32_bf16 v[62:65], v[34:37], v[70:73], v[74:77]
	v_exp_f32_e32 v40, v40
	v_cvt_pk_bf16_f32 v8, v54, v55
	v_mfma_f32_16x16x32_bf16 v[70:73], v[30:33], v[70:73], v[78:81]
	v_exp_f32_e32 v41, v41
	v_cvt_pk_bf16_f32 v9, v56, v57
	s_waitcnt lgkmcnt(10)
	v_mfma_f32_16x16x32_bf16 v[54:57], v[34:37], v[82:85], v[86:89]
	v_exp_f32_e32 v42, v42
	v_cvt_pk_bf16_f32 v2, v50, v51
	v_mfma_f32_16x16x32_bf16 v[74:77], v[30:33], v[82:85], v[90:93]
	v_exp_f32_e32 v43, v43
	v_cvt_pk_bf16_f32 v3, v52, v53
	s_waitcnt lgkmcnt(8)
	v_mfma_f32_16x16x32_bf16 v[50:53], v[34:37], v[136:139], v[144:147]
	v_exp_f32_e32 v44, v44
	v_cvt_pk_bf16_f32 v4, v46, v47
	v_mfma_f32_16x16x32_bf16 v[78:81], v[30:33], v[136:139], v[94:97]
	v_exp_f32_e32 v45, v45
	v_cvt_pk_bf16_f32 v5, v48, v49
	s_waitcnt lgkmcnt(6)
	v_mfma_f32_16x16x32_bf16 v[46:49], v[34:37], v[152:155], v[128:131]
	v_exp_f32_e32 v10, v10
	v_mfma_f32_16x16x32_bf16 v[82:85], v[30:33], v[152:155], v[132:135]
	v_exp_f32_e32 v11, v11
	s_nop 0
	v_exp_f32_e32 v12, v12
	s_waitcnt lgkmcnt(4)
	v_mfma_f32_16x16x32_bf16 v[86:89], v[34:37], v[156:159], v[120:123]
	s_nop 0
	v_exp_f32_e32 v13, v13
	v_mfma_f32_16x16x32_bf16 v[90:93], v[30:33], v[156:159], v[124:127]
	v_exp_f32_e32 v14, v14
	s_waitcnt lgkmcnt(2)
	v_mfma_f32_16x16x32_bf16 v[94:97], v[34:37], v[160:163], v[106:109]
	s_nop 0
	v_exp_f32_e32 v15, v15
	v_mfma_f32_16x16x32_bf16 v[106:109], v[30:33], v[160:163], v[110:113]
	s_waitcnt lgkmcnt(0)
	v_mfma_f32_16x16x32_bf16 v[34:37], v[34:37], v[148:151], v[98:101]
	v_exp_f32_e32 v16, v16
	v_mfma_f32_16x16x32_bf16 v[30:33], v[30:33], v[148:151], v[102:105]
	v_exp_f32_e32 v17, v17
	v_cvt_pk_bf16_f32 v98, v38, v39
	v_cvt_pk_bf16_f32 v99, v40, v41
	v_cvt_pk_bf16_f32 v100, v10, v11
	v_cvt_pk_bf16_f32 v101, v12, v13
	v_cvt_pk_bf16_f32 v102, v42, v43
	v_cvt_pk_bf16_f32 v103, v44, v45
	v_cvt_pk_bf16_f32 v104, v14, v15
	v_cvt_pk_bf16_f32 v105, v16, v17
	s_waitcnt vmcnt(0) lgkmcnt(0)
	s_barrier
; #define MF16(a, b, c) __builtin_amdgcn_mfma_f32_16x16x32_bf16(a, b, c, 0, 0, 0)
; #define MF16(a, b, c) __builtin_amdgcn_mfma_f32_16x16x32_bf16(a, b, c, 0, 0, 0)
; #define VRD16(f) do { vlo[f] = vtr(vpb[(f) & 3] + vo_ + (((f) >> 2) & 1) * 8192 + ((f) >> 3) * 4096); vhi[f] = vtr(vpb[(f) & 3] + vo_ + (((f) >> 2) & 1) * 8192 + ((f) >> 3) * 4096 + 2048); } while (0)
; __device__ __forceinline__ void attn_unit_d16(const UnitDesc& U, char* shm, float lam, const float* subw) {
;     ...
;     { constexpr int vo_ = 3 * VS;
; #pragma unroll
;       for (int f = 0; f < 16; ++f) { VRD16(f);
; #pragma unroll
;           for (int qt = 0; qt < 2; ++qt) o[qt][f & 7] = MF16(__builtin_bit_cast(bf16x8, pa[qt][f >> 3]), VFR16(f), o[qt][f & 7]); }
; #pragma unroll
;       for (int qt = 0; qt < 2; ++qt)
; #pragma unroll
;           for (int ks = 0; ks < 2; ++ks) ls[qt] = MF16(__builtin_bit_cast(bf16x8, pa[qt][ks]), onesb, ls[qt]); }
;     ...
;             for (int r = 0; r < 4; ++r) { const float sc = __builtin_amdgcn_rcpf(ls[qt][r]) * lam; const int row = 16 * qt + 4 * g_e + r;
	ds_read_b64_tr_b16 v[10:11], v203 offset:49152
	ds_read_b64_tr_b16 v[12:13], v203 offset:51200
	ds_read_b64_tr_b16 v[14:15], v203 offset:53248
	ds_read_b64_tr_b16 v[16:17], v203 offset:55296
	v_mov_b32_e32 v1, v193
	s_lshl_b32 s10, s13, 14
	s_waitcnt lgkmcnt(2)
	v_mfma_f32_16x16x32_bf16 v[38:41], v[6:9], v[10:13], v[58:61]
	ds_read_b64_tr_b16 v[42:43], v204 offset:49152
	ds_read_b64_tr_b16 v[44:45], v204 offset:51200
	s_nop 0
	ds_read_b64_tr_b16 v[58:59], v204 offset:53248
	ds_read_b64_tr_b16 v[60:61], v204 offset:55296
	s_and_b32 s10, s10, 0xc000
	s_add_i32 s10, s10, 0
	v_mfma_f32_16x16x32_bf16 v[10:13], v[2:5], v[10:13], v[66:69]
	s_nop 2
	ds_read_b64_tr_b16 v[66:67], v205 offset:49152
	ds_read_b64_tr_b16 v[68:69], v205 offset:51200
	ds_read_b64_tr_b16 v[110:111], v205 offset:53248
	ds_read_b64_tr_b16 v[112:113], v205 offset:55296
	s_cmpk_gt_u32 s12, 0xff
	s_waitcnt lgkmcnt(6)
	v_mfma_f32_16x16x32_bf16 v[62:65], v[6:9], v[42:45], v[62:65]
	v_mfma_f32_16x16x32_bf16 v[42:45], v[2:5], v[42:45], v[70:73]
	s_nop 2
	ds_read_b64_tr_b16 v[70:71], v206 offset:49152
	ds_read_b64_tr_b16 v[72:73], v206 offset:51200
	ds_read_b64_tr_b16 v[116:117], v206 offset:53248
	ds_read_b64_tr_b16 v[118:119], v206 offset:55296
	s_waitcnt lgkmcnt(2)
	v_mfma_f32_16x16x32_bf16 v[50:53], v[6:9], v[70:73], v[50:53]
	v_mfma_f32_16x16x32_bf16 v[78:81], v[2:5], v[70:73], v[78:81]
	ds_read_b64_tr_b16 v[70:71], v203 offset:57344
	ds_read_b64_tr_b16 v[72:73], v203 offset:59392
	ds_read_b64_tr_b16 v[120:121], v203 offset:61440
	ds_read_b64_tr_b16 v[122:123], v203 offset:63488
	s_waitcnt lgkmcnt(2)
	v_mfma_f32_16x16x32_bf16 v[46:49], v[6:9], v[70:73], v[46:49]
	v_mfma_f32_16x16x32_bf16 v[82:85], v[2:5], v[70:73], v[82:85]
	ds_read_b64_tr_b16 v[70:71], v204 offset:57344
	ds_read_b64_tr_b16 v[72:73], v204 offset:59392
	ds_read_b64_tr_b16 v[124:125], v204 offset:61440
	ds_read_b64_tr_b16 v[126:127], v204 offset:63488
	s_waitcnt lgkmcnt(2)
	v_mfma_f32_16x16x32_bf16 v[86:89], v[6:9], v[70:73], v[86:89]
	v_mfma_f32_16x16x32_bf16 v[90:93], v[2:5], v[70:73], v[90:93]
	ds_read_b64_tr_b16 v[70:71], v205 offset:57344
	ds_read_b64_tr_b16 v[72:73], v205 offset:59392
	ds_read_b64_tr_b16 v[128:129], v205 offset:61440
	ds_read_b64_tr_b16 v[130:131], v205 offset:63488
	s_waitcnt lgkmcnt(2)
	v_mfma_f32_16x16x32_bf16 v[94:97], v[6:9], v[70:73], v[94:97]
	v_mfma_f32_16x16x32_bf16 v[106:109], v[2:5], v[70:73], v[106:109]
	ds_read_b64_tr_b16 v[70:71], v206 offset:57344
	ds_read_b64_tr_b16 v[72:73], v206 offset:59392
	ds_read_b64_tr_b16 v[132:133], v206 offset:61440
	ds_read_b64_tr_b16 v[134:135], v206 offset:63488
	s_waitcnt lgkmcnt(0)
	s_barrier
	v_mfma_f32_16x16x32_bf16 v[54:57], v[6:9], v[66:69], v[54:57]
	v_mfma_f32_16x16x32_bf16 v[66:69], v[2:5], v[66:69], v[74:77]
	s_waitcnt lgkmcnt(2)
	v_mfma_f32_16x16x32_bf16 v[136:139], v[6:9], v[70:73], v[34:37]
	v_mfma_f32_16x16x32_bf16 v[140:143], v[2:5], v[70:73], v[30:33]
	v_mfma_f32_16x16x32_bf16 v[6:9], v[6:9], v[26:29], v[18:21]
	v_mfma_f32_16x16x32_bf16 v[2:5], v[2:5], v[26:29], v[22:25]
	v_mfma_f32_16x16x32_bf16 v[74:77], v[98:101], v[58:61], v[62:65]
	v_mfma_f32_16x16x32_bf16 v[42:45], v[102:105], v[58:61], v[42:45]
	v_mfma_f32_16x16x32_bf16 v[58:61], v[98:101], v[110:113], v[54:57]
	v_mfma_f32_16x16x32_bf16 v[54:57], v[98:101], v[124:127], v[86:89]
	v_mfma_f32_16x16x32_bf16 v[86:89], v[98:101], v[26:29], v[6:9]
	v_mfma_f32_16x16x32_bf16 v[2:5], v[102:105], v[26:29], v[2:5]
	v_mfma_f32_16x16x32_bf16 v[70:73], v[98:101], v[14:17], v[38:41]
	s_nop 5
	v_mov_b32_dpp v86, v86 row_newbcast:0 row_mask:0xf bank_mask:0xf
	v_mov_b32_dpp v87, v87 row_newbcast:0 row_mask:0xf bank_mask:0xf
	v_mov_b32_dpp v88, v88 row_newbcast:0 row_mask:0xf bank_mask:0xf
	v_mov_b32_dpp v89, v89 row_newbcast:0 row_mask:0xf bank_mask:0xf
	v_rcp_f32_e32 v21, v86
	v_rcp_f32_e32 v20, v87
	v_rcp_f32_e32 v19, v88
	v_mfma_f32_16x16x32_bf16 v[38:41], v[102:105], v[14:17], v[10:13]
	v_rcp_f32_e32 v18, v89
	v_mov_b32_dpp v2, v2 row_newbcast:0 row_mask:0xf bank_mask:0xf
	v_mov_b32_dpp v3, v3 row_newbcast:0 row_mask:0xf bank_mask:0xf
	v_mov_b32_dpp v4, v4 row_newbcast:0 row_mask:0xf bank_mask:0xf
	v_mov_b32_dpp v5, v5 row_newbcast:0 row_mask:0xf bank_mask:0xf
	v_rcp_f32_e32 v9, v2
	v_rcp_f32_e32 v8, v3
	v_mfma_f32_16x16x32_bf16 v[10:13], v[102:105], v[120:123], v[82:85]
	s_nop 2
	v_and_b32_e32 v84, 15, v1
	v_ashrrev_i32_e32 v82, 4, v1
	v_lshlrev_b32_e32 v1, 11, v82
	v_lshlrev_b32_e32 v6, 2, v84
	v_mfma_f32_16x16x32_bf16 v[30:33], v[102:105], v[110:113], v[66:69]
	v_add3_u32 v7, s10, v6, v1
	v_rcp_f32_e32 v6, v4
	v_rcp_f32_e32 v1, v5
	v_mfma_f32_16x16x32_bf16 v[62:65], v[98:101], v[116:119], v[50:53]
	v_mfma_f32_16x16x32_bf16 v[34:37], v[102:105], v[116:119], v[78:81]
	v_mfma_f32_16x16x32_bf16 v[66:69], v[98:101], v[120:123], v[46:49]
	v_mfma_f32_16x16x32_bf16 v[14:17], v[102:105], v[124:127], v[90:93]
	v_mfma_f32_16x16x32_bf16 v[50:53], v[98:101], v[128:131], v[94:97]
	v_mfma_f32_16x16x32_bf16 v[46:49], v[102:105], v[128:131], v[106:109]
	s_waitcnt lgkmcnt(0)
	v_mfma_f32_16x16x32_bf16 v[78:81], v[98:101], v[132:135], v[136:139]
	v_mfma_f32_16x16x32_bf16 v[2:5], v[102:105], v[132:135], v[140:143]
	s_cbranch_scc0 .LBB0_447
; __device__ __forceinline__ void attn_unit_d16(const UnitDesc& U, char* shm, float lam, const float* subw) {
;     ...
;     if (wid >= 4) {
; #pragma unroll
;         for (int qt = 0; qt < 2; ++qt)
; #pragma unroll
;             for (int r = 0; r < 4; ++r) { const float sc = __builtin_amdgcn_rcpf(ls[qt][r]) * lam; const int row = 16 * qt + 4 * g_e + r;
; #pragma unroll
;                 for (int dt = 0; dt < 8; ++dt) X[row * 128 + 16 * dt + c16_e] = o[qt][dt][r] * sc; }
;     }
	v_mul_f32_e32 v22, v181, v21
	v_mul_f32_e32 v23, v70, v22
	v_mul_f32_e32 v24, v74, v22
	ds_write2_b32 v7, v23, v24 offset1:16
	v_mul_f32_e32 v23, v58, v22
	v_mul_f32_e32 v24, v62, v22
	ds_write2_b32 v7, v23, v24 offset0:32 offset1:48
	v_mul_f32_e32 v23, v66, v22
	v_mul_f32_e32 v24, v54, v22
	ds_write2_b32 v7, v23, v24 offset0:64 offset1:80
	v_mul_f32_e32 v23, v50, v22
	v_mul_f32_e32 v22, v78, v22
	ds_write2_b32 v7, v23, v22 offset0:96 offset1:112
	v_mul_f32_e32 v22, v181, v20
	v_mul_f32_e32 v23, v71, v22
	v_mul_f32_e32 v24, v75, v22
	ds_write2_b32 v7, v23, v24 offset0:128 offset1:144
	v_mul_f32_e32 v23, v59, v22
	v_mul_f32_e32 v24, v63, v22
	ds_write2_b32 v7, v23, v24 offset0:160 offset1:176
	v_mul_f32_e32 v23, v67, v22
	v_mul_f32_e32 v24, v55, v22
	ds_write2_b32 v7, v23, v24 offset0:192 offset1:208
	v_mul_f32_e32 v23, v51, v22
	v_mul_f32_e32 v22, v79, v22
	ds_write2_b32 v7, v23, v22 offset0:224 offset1:240
	v_mul_f32_e32 v22, v181, v19
	v_mul_f32_e32 v23, v72, v22
	v_mul_f32_e32 v24, v76, v22
	v_add_u32_e32 v25, 0x400, v7
	ds_write2_b32 v25, v23, v24 offset1:16
	v_mul_f32_e32 v23, v60, v22
	v_mul_f32_e32 v24, v64, v22
	ds_write2_b32 v25, v23, v24 offset0:32 offset1:48
	v_mul_f32_e32 v23, v68, v22
	v_mul_f32_e32 v24, v56, v22
	ds_write2_b32 v25, v23, v24 offset0:64 offset1:80
	v_mul_f32_e32 v23, v52, v22
	v_mul_f32_e32 v22, v80, v22
	ds_write2_b32 v25, v23, v22 offset0:96 offset1:112
	v_mul_f32_e32 v22, v181, v18
	v_mul_f32_e32 v23, v73, v22
	v_mul_f32_e32 v24, v77, v22
	ds_write2_b32 v25, v23, v24 offset0:128 offset1:144
	v_mul_f32_e32 v23, v61, v22
	v_mul_f32_e32 v24, v65, v22
	ds_write2_b32 v25, v23, v24 offset0:160 offset1:176
	v_mul_f32_e32 v23, v69, v22
	v_mul_f32_e32 v24, v57, v22
	ds_write2_b32 v25, v23, v24 offset0:192 offset1:208
	v_mul_f32_e32 v23, v53, v22
	v_mul_f32_e32 v22, v81, v22
	ds_write2_b32 v25, v23, v22 offset0:224 offset1:240
	v_mul_f32_e32 v22, v181, v9
	v_mul_f32_e32 v23, v38, v22
	v_mul_f32_e32 v24, v42, v22
	v_add_u32_e32 v25, 0x2000, v7
	ds_write2_b32 v25, v23, v24 offset1:16
	v_mul_f32_e32 v23, v30, v22
	v_mul_f32_e32 v24, v34, v22
	ds_write2_b32 v25, v23, v24 offset0:32 offset1:48
	v_mul_f32_e32 v23, v10, v22
	v_mul_f32_e32 v24, v14, v22
	ds_write2_b32 v25, v23, v24 offset0:64 offset1:80
	v_mul_f32_e32 v23, v46, v22
	v_mul_f32_e32 v22, v2, v22
	ds_write2_b32 v25, v23, v22 offset0:96 offset1:112
	v_mul_f32_e32 v22, v181, v8
	v_mul_f32_e32 v23, v39, v22
	v_mul_f32_e32 v24, v43, v22
	ds_write2_b32 v25, v23, v24 offset0:128 offset1:144
	v_mul_f32_e32 v23, v31, v22
	v_mul_f32_e32 v24, v35, v22
	ds_write2_b32 v25, v23, v24 offset0:160 offset1:176
	v_mul_f32_e32 v23, v11, v22
	v_mul_f32_e32 v24, v15, v22
	ds_write2_b32 v25, v23, v24 offset0:192 offset1:208
	v_mul_f32_e32 v23, v47, v22
	v_mul_f32_e32 v22, v3, v22
	ds_write2_b32 v25, v23, v22 offset0:224 offset1:240
	v_mul_f32_e32 v22, v181, v6
	v_mul_f32_e32 v23, v40, v22
	v_mul_f32_e32 v24, v44, v22
	v_add_u32_e32 v25, 0x2400, v7
	ds_write2_b32 v25, v23, v24 offset1:16
	v_mul_f32_e32 v23, v32, v22
	v_mul_f32_e32 v24, v36, v22
	ds_write2_b32 v25, v23, v24 offset0:32 offset1:48
	v_mul_f32_e32 v23, v12, v22
	v_mul_f32_e32 v24, v16, v22
	ds_write2_b32 v25, v23, v24 offset0:64 offset1:80
	v_mul_f32_e32 v23, v48, v22
	v_mul_f32_e32 v22, v4, v22
	ds_write2_b32 v25, v23, v22 offset0:96 offset1:112
	v_mul_f32_e32 v22, v181, v1
	v_mul_f32_e32 v23, v41, v22
	v_mul_f32_e32 v24, v45, v22
	ds_write2_b32 v25, v23, v24 offset0:128 offset1:144
	v_mul_f32_e32 v23, v33, v22
	v_mul_f32_e32 v24, v37, v22
	ds_write2_b32 v25, v23, v24 offset0:160 offset1:176
	v_mul_f32_e32 v23, v13, v22
	v_mul_f32_e32 v24, v17, v22
	ds_write2_b32 v25, v23, v24 offset0:192 offset1:208
	v_mul_f32_e32 v23, v49, v22
	v_mul_f32_e32 v22, v5, v22
	ds_write2_b32 v25, v23, v22 offset0:224 offset1:240
